# gelu_tanh epilogues: accumulator quads evaluated together with packed f32 math instead of four serial chains through one temporary
# baseline (speedup 1.0000x reference)
.LBB0_893:
	s_add_u32 s10, s8, 0xfffc0080
	s_addc_u32 s11, s9, -1
	s_add_i32 s34, 0, 0x10000
	v_add_u32_e32 v154, s34, v140
	ds_read_b128 v[142:145], v154
	ds_read_b128 v[146:149], v154 offset:1024
	ds_read_b128 v[150:153], v154 offset:2048
	ds_read_b128 v[154:157], v154 offset:3072
	s_cmp_eq_u32 s53, 12
	s_cselect_b32 s15, s5, s11
	s_cselect_b32 s14, s39, s10
	s_cselect_b32 s11, s48, s52
	s_cselect_b32 s10, s50, s51
	v_lshl_add_u64 v[162:163], s[8:9], 0, v[138:139]
	s_add_i32 m0, s7, 0xc000
	ds_read_b128 v[158:161], v141
	ds_read_b128 v[166:169], v141 offset:1024
	ds_read_b128 v[170:173], v141 offset:2048
	ds_read_b128 v[174:177], v141 offset:3072
	ds_read_b128 v[178:181], v141 offset:4096
	ds_read_b128 v[182:185], v141 offset:5120
	ds_read_b128 v[198:201], v141 offset:6144
	ds_read_b128 v[202:205], v141 offset:7168
	global_load_lds_dwordx4 v[162:163], off
	v_lshl_add_u64 v[162:163], s[8:9], 0, v[136:137]
	s_add_i32 m0, s7, 0xe000
	s_nop 0
	global_load_lds_dwordx4 v[162:163], off
	s_waitcnt lgkmcnt(8)
	s_barrier
	s_waitcnt lgkmcnt(0)
	s_setprio 1
	s_waitcnt lgkmcnt(0)
	v_mfma_f32_16x16x32_bf16 v[124:127], v[142:145], v[158:161], v[124:127]
	v_mfma_f32_16x16x32_bf16 v[120:123], v[150:153], v[158:161], v[120:123]
	v_mfma_f32_16x16x32_bf16 v[108:111], v[142:145], v[170:173], v[108:111]
	v_mfma_f32_16x16x32_bf16 v[104:107], v[150:153], v[170:173], v[104:107]
	v_mfma_f32_16x16x32_bf16 v[92:95], v[142:145], v[178:181], v[92:95]
	v_mfma_f32_16x16x32_bf16 v[88:91], v[150:153], v[178:181], v[88:91]
	v_mfma_f32_16x16x32_bf16 v[76:79], v[142:145], v[198:201], v[76:79]
	v_mfma_f32_16x16x32_bf16 v[72:75], v[150:153], v[198:201], v[72:75]
	v_mfma_f32_16x16x32_bf16 v[124:127], v[146:149], v[166:169], v[124:127]
	v_mfma_f32_16x16x32_bf16 v[120:123], v[154:157], v[166:169], v[120:123]
	v_mfma_f32_16x16x32_bf16 v[108:111], v[146:149], v[174:177], v[108:111]
	v_mfma_f32_16x16x32_bf16 v[104:107], v[154:157], v[174:177], v[104:107]
	v_mfma_f32_16x16x32_bf16 v[92:95], v[146:149], v[182:185], v[92:95]
	v_mfma_f32_16x16x32_bf16 v[88:91], v[154:157], v[182:185], v[88:91]
	v_mfma_f32_16x16x32_bf16 v[76:79], v[146:149], v[202:205], v[76:79]
	v_mfma_f32_16x16x32_bf16 v[72:75], v[154:157], v[202:205], v[72:75]
	s_setprio 0
	s_barrier
	s_add_i32 s59, 0, 0x14000
	v_add_u32_e32 v162, s59, v140
	s_add_i32 s34, s34, s6
	ds_read_b128 v[206:209], v162
	ds_read_b128 v[210:213], v162 offset:1024
	ds_read_b128 v[214:217], v162 offset:2048
	ds_read_b128 v[218:221], v162 offset:3072
	v_lshl_add_u64 v[162:163], s[10:11], 0, v[134:135]
	s_mov_b32 m0, s34
	s_nop 0
	global_load_lds_dwordx4 v[162:163], off
	v_lshl_add_u64 v[162:163], s[10:11], 0, v[130:131]
	s_add_i32 m0, s34, 0x2000
	s_nop 0
	global_load_lds_dwordx4 v[162:163], off
	s_barrier
	s_waitcnt lgkmcnt(0)
	s_setprio 1
	s_waitcnt lgkmcnt(0)
	v_mfma_f32_16x16x32_bf16 v[116:119], v[206:209], v[158:161], v[116:119]
	v_mfma_f32_16x16x32_bf16 v[112:115], v[214:217], v[158:161], v[112:115]
	v_mfma_f32_16x16x32_bf16 v[100:103], v[206:209], v[170:173], v[100:103]
	v_mfma_f32_16x16x32_bf16 v[96:99], v[214:217], v[170:173], v[96:99]
	v_mfma_f32_16x16x32_bf16 v[84:87], v[206:209], v[178:181], v[84:87]
	v_mfma_f32_16x16x32_bf16 v[80:83], v[214:217], v[178:181], v[80:83]
	v_mfma_f32_16x16x32_bf16 v[68:71], v[206:209], v[198:201], v[68:71]
	v_mfma_f32_16x16x32_bf16 v[64:67], v[214:217], v[198:201], v[64:67]
	v_mfma_f32_16x16x32_bf16 v[116:119], v[210:213], v[166:169], v[116:119]
	v_mfma_f32_16x16x32_bf16 v[112:115], v[218:221], v[166:169], v[112:115]
	v_mfma_f32_16x16x32_bf16 v[100:103], v[210:213], v[174:177], v[100:103]
	v_mfma_f32_16x16x32_bf16 v[96:99], v[218:221], v[174:177], v[96:99]
	v_mfma_f32_16x16x32_bf16 v[84:87], v[210:213], v[182:185], v[84:87]
	v_mfma_f32_16x16x32_bf16 v[80:83], v[218:221], v[182:185], v[80:83]
	v_mfma_f32_16x16x32_bf16 v[68:71], v[210:213], v[202:205], v[68:71]
	v_mfma_f32_16x16x32_bf16 v[64:67], v[218:221], v[202:205], v[64:67]
	s_setprio 0
	s_mov_b32 m0, s7
	v_lshl_add_u64 v[162:163], s[14:15], 0, v[132:133]
	s_barrier
	ds_read_b128 v[158:161], v141 offset:16384
	ds_read_b128 v[166:169], v141 offset:17408
	ds_read_b128 v[170:173], v141 offset:18432
	ds_read_b128 v[174:177], v141 offset:19456
	ds_read_b128 v[178:181], v141 offset:20480
	ds_read_b128 v[182:185], v141 offset:21504
	ds_read_b128 v[198:201], v141 offset:22528
	ds_read_b128 v[202:205], v141 offset:23552
	global_load_lds_dwordx4 v[162:163], off
	v_lshl_add_u64 v[186:187], s[14:15], 0, v[128:129]
	s_mov_b32 m0, s16
	s_nop 0
	global_load_lds_dwordx4 v[186:187], off
	s_barrier
	s_waitcnt lgkmcnt(0)
	s_setprio 1
	s_waitcnt lgkmcnt(0)
	v_mfma_f32_16x16x32_bf16 v[60:63], v[142:145], v[158:161], v[60:63]
	v_mfma_f32_16x16x32_bf16 v[56:59], v[150:153], v[158:161], v[56:59]
	v_mfma_f32_16x16x32_bf16 v[44:47], v[142:145], v[170:173], v[44:47]
	v_mfma_f32_16x16x32_bf16 v[40:43], v[150:153], v[170:173], v[40:43]
	v_mfma_f32_16x16x32_bf16 v[28:31], v[142:145], v[178:181], v[28:31]
	v_mfma_f32_16x16x32_bf16 v[24:27], v[150:153], v[178:181], v[24:27]
	v_mfma_f32_16x16x32_bf16 v[12:15], v[142:145], v[198:201], v[12:15]
	v_mfma_f32_16x16x32_bf16 v[8:11], v[150:153], v[198:201], v[8:11]
	v_mfma_f32_16x16x32_bf16 v[60:63], v[146:149], v[166:169], v[60:63]
	v_mfma_f32_16x16x32_bf16 v[56:59], v[154:157], v[166:169], v[56:59]
	v_mfma_f32_16x16x32_bf16 v[44:47], v[146:149], v[174:177], v[44:47]
	v_mfma_f32_16x16x32_bf16 v[40:43], v[154:157], v[174:177], v[40:43]
	v_mfma_f32_16x16x32_bf16 v[28:31], v[146:149], v[182:185], v[28:31]
	v_mfma_f32_16x16x32_bf16 v[24:27], v[154:157], v[182:185], v[24:27]
	v_mfma_f32_16x16x32_bf16 v[12:15], v[146:149], v[202:205], v[12:15]
	v_mfma_f32_16x16x32_bf16 v[8:11], v[154:157], v[202:205], v[8:11]
	s_setprio 0
	s_barrier
	s_add_u32 s34, s10, 0x4000
	s_addc_u32 s35, s11, 0
	s_add_i32 s59, s59, s6
	v_lshl_add_u64 v[142:143], s[34:35], 0, v[134:135]
	s_mov_b32 m0, s59
	s_nop 0
	global_load_lds_dwordx4 v[142:143], off
	v_lshl_add_u64 v[142:143], s[34:35], 0, v[130:131]
	s_add_i32 m0, s59, 0x2000
	s_nop 0
	global_load_lds_dwordx4 v[142:143], off
	s_waitcnt vmcnt(6)
	s_barrier
	s_setprio 1
	v_mfma_f32_16x16x32_bf16 v[52:55], v[206:209], v[158:161], v[52:55]
	v_mfma_f32_16x16x32_bf16 v[48:51], v[214:217], v[158:161], v[48:51]
	v_mfma_f32_16x16x32_bf16 v[36:39], v[206:209], v[170:173], v[36:39]
	v_mfma_f32_16x16x32_bf16 v[32:35], v[214:217], v[170:173], v[32:35]
	v_mfma_f32_16x16x32_bf16 v[20:23], v[206:209], v[178:181], v[20:23]
	v_mfma_f32_16x16x32_bf16 v[16:19], v[214:217], v[178:181], v[16:19]
	v_mfma_f32_16x16x32_bf16 v[4:7], v[206:209], v[198:201], v[4:7]
	v_mfma_f32_16x16x32_bf16 v[0:3], v[214:217], v[198:201], v[0:3]
	v_mfma_f32_16x16x32_bf16 v[52:55], v[210:213], v[166:169], v[52:55]
	v_mfma_f32_16x16x32_bf16 v[48:51], v[218:221], v[166:169], v[48:51]
	v_mfma_f32_16x16x32_bf16 v[36:39], v[210:213], v[174:177], v[36:39]
	v_mfma_f32_16x16x32_bf16 v[32:35], v[218:221], v[174:177], v[32:35]
	v_mfma_f32_16x16x32_bf16 v[20:23], v[210:213], v[182:185], v[20:23]
	v_mfma_f32_16x16x32_bf16 v[16:19], v[218:221], v[182:185], v[16:19]
	v_mfma_f32_16x16x32_bf16 v[4:7], v[210:213], v[202:205], v[4:7]
	v_mfma_f32_16x16x32_bf16 v[0:3], v[218:221], v[202:205], v[0:3]
	s_setprio 0
	s_add_i32 s34, 0, 0x18000
	v_add_u32_e32 v154, s34, v140
	s_barrier
	ds_read_b128 v[142:145], v154
	ds_read_b128 v[146:149], v154 offset:1024
	ds_read_b128 v[150:153], v154 offset:2048
	ds_read_b128 v[154:157], v154 offset:3072
	s_add_u32 s14, s14, 0x40000
	s_addc_u32 s15, s15, 0
	s_mov_b32 m0, s17
	v_lshl_add_u64 v[206:207], s[14:15], 0, v[132:133]
	ds_read_b128 v[158:161], v141 offset:32768
	ds_read_b128 v[166:169], v141 offset:33792
	ds_read_b128 v[170:173], v141 offset:34816
	ds_read_b128 v[174:177], v141 offset:35840
	ds_read_b128 v[178:181], v141 offset:36864
	ds_read_b128 v[182:185], v141 offset:37888
	ds_read_b128 v[198:201], v141 offset:38912
	ds_read_b128 v[202:205], v141 offset:39936
	global_load_lds_dwordx4 v[206:207], off
	v_lshl_add_u64 v[206:207], s[14:15], 0, v[128:129]
	s_mov_b32 m0, s22
	s_nop 0
	global_load_lds_dwordx4 v[206:207], off
	s_waitcnt lgkmcnt(8)
	s_barrier
	s_waitcnt lgkmcnt(0)
	s_setprio 1
	s_waitcnt lgkmcnt(0)
	v_mfma_f32_16x16x32_bf16 v[124:127], v[142:145], v[158:161], v[124:127]
	v_mfma_f32_16x16x32_bf16 v[120:123], v[150:153], v[158:161], v[120:123]
	v_mfma_f32_16x16x32_bf16 v[108:111], v[142:145], v[170:173], v[108:111]
	v_mfma_f32_16x16x32_bf16 v[104:107], v[150:153], v[170:173], v[104:107]
	v_mfma_f32_16x16x32_bf16 v[92:95], v[142:145], v[178:181], v[92:95]
	v_mfma_f32_16x16x32_bf16 v[88:91], v[150:153], v[178:181], v[88:91]
	v_mfma_f32_16x16x32_bf16 v[76:79], v[142:145], v[198:201], v[76:79]
	v_mfma_f32_16x16x32_bf16 v[72:75], v[150:153], v[198:201], v[72:75]
	v_mfma_f32_16x16x32_bf16 v[124:127], v[146:149], v[166:169], v[124:127]
	v_mfma_f32_16x16x32_bf16 v[120:123], v[154:157], v[166:169], v[120:123]
	v_mfma_f32_16x16x32_bf16 v[108:111], v[146:149], v[174:177], v[108:111]
	v_mfma_f32_16x16x32_bf16 v[104:107], v[154:157], v[174:177], v[104:107]
	v_mfma_f32_16x16x32_bf16 v[92:95], v[146:149], v[182:185], v[92:95]
	v_mfma_f32_16x16x32_bf16 v[88:91], v[154:157], v[182:185], v[88:91]
	v_mfma_f32_16x16x32_bf16 v[76:79], v[146:149], v[202:205], v[76:79]
	v_mfma_f32_16x16x32_bf16 v[72:75], v[154:157], v[202:205], v[72:75]
	s_setprio 0
	s_barrier
	s_add_i32 s35, 0, 0x1c000
	s_add_u32 s14, s10, 0x8000
	s_addc_u32 s15, s11, 0
	s_add_i32 s34, s34, s6
	v_add_u32_e32 v164, s35, v140
	v_lshl_add_u64 v[222:223], s[14:15], 0, v[134:135]
	s_mov_b32 m0, s34
	ds_read_b128 v[206:209], v164
	ds_read_b128 v[210:213], v164 offset:1024
	ds_read_b128 v[214:217], v164 offset:2048
	ds_read_b128 v[218:221], v164 offset:3072
	global_load_lds_dwordx4 v[222:223], off
	v_lshl_add_u64 v[222:223], s[14:15], 0, v[130:131]
	s_add_i32 m0, s34, 0x2000
	s_nop 0
	global_load_lds_dwordx4 v[222:223], off
	s_barrier
	s_waitcnt lgkmcnt(0)
	s_setprio 1
	s_waitcnt lgkmcnt(0)
	v_mfma_f32_16x16x32_bf16 v[116:119], v[206:209], v[158:161], v[116:119]
	v_mfma_f32_16x16x32_bf16 v[112:115], v[214:217], v[158:161], v[112:115]
	v_mfma_f32_16x16x32_bf16 v[100:103], v[206:209], v[170:173], v[100:103]
	v_mfma_f32_16x16x32_bf16 v[96:99], v[214:217], v[170:173], v[96:99]
	v_mfma_f32_16x16x32_bf16 v[84:87], v[206:209], v[178:181], v[84:87]
	v_mfma_f32_16x16x32_bf16 v[80:83], v[214:217], v[178:181], v[80:83]
	v_mfma_f32_16x16x32_bf16 v[68:71], v[206:209], v[198:201], v[68:71]
	v_mfma_f32_16x16x32_bf16 v[64:67], v[214:217], v[198:201], v[64:67]
	v_mfma_f32_16x16x32_bf16 v[116:119], v[210:213], v[166:169], v[116:119]
	v_mfma_f32_16x16x32_bf16 v[112:115], v[218:221], v[166:169], v[112:115]
	v_mfma_f32_16x16x32_bf16 v[100:103], v[210:213], v[174:177], v[100:103]
	v_mfma_f32_16x16x32_bf16 v[96:99], v[218:221], v[174:177], v[96:99]
	v_mfma_f32_16x16x32_bf16 v[84:87], v[210:213], v[182:185], v[84:87]
	v_mfma_f32_16x16x32_bf16 v[80:83], v[218:221], v[182:185], v[80:83]
	v_mfma_f32_16x16x32_bf16 v[68:71], v[210:213], v[202:205], v[68:71]
	v_mfma_f32_16x16x32_bf16 v[64:67], v[218:221], v[202:205], v[64:67]
	s_setprio 0
	s_mov_b32 m0, s25
	v_lshl_add_u64 v[162:163], v[162:163], 0, s[18:19]
	s_barrier
	ds_read_b128 v[158:161], v141 offset:49152
	ds_read_b128 v[166:169], v141 offset:50176
	ds_read_b128 v[170:173], v141 offset:51200
	ds_read_b128 v[174:177], v141 offset:52224
	ds_read_b128 v[178:181], v141 offset:53248
	ds_read_b128 v[182:185], v141 offset:54272
	ds_read_b128 v[198:201], v141 offset:55296
	ds_read_b128 v[202:205], v141 offset:56320
	global_load_lds_dwordx4 v[162:163], off
	v_lshl_add_u64 v[162:163], v[186:187], 0, s[18:19]
	s_mov_b32 m0, s27
	s_nop 0
	global_load_lds_dwordx4 v[162:163], off
	s_barrier
	s_waitcnt lgkmcnt(0)
	s_setprio 1
	s_waitcnt lgkmcnt(0)
	v_mfma_f32_16x16x32_bf16 v[60:63], v[142:145], v[158:161], v[60:63]
	v_mfma_f32_16x16x32_bf16 v[56:59], v[150:153], v[158:161], v[56:59]
	v_mfma_f32_16x16x32_bf16 v[44:47], v[142:145], v[170:173], v[44:47]
	v_mfma_f32_16x16x32_bf16 v[40:43], v[150:153], v[170:173], v[40:43]
	v_mfma_f32_16x16x32_bf16 v[28:31], v[142:145], v[178:181], v[28:31]
	v_mfma_f32_16x16x32_bf16 v[24:27], v[150:153], v[178:181], v[24:27]
	v_mfma_f32_16x16x32_bf16 v[12:15], v[142:145], v[198:201], v[12:15]
	v_mfma_f32_16x16x32_bf16 v[8:11], v[150:153], v[198:201], v[8:11]
	v_mfma_f32_16x16x32_bf16 v[60:63], v[146:149], v[166:169], v[60:63]
	v_mfma_f32_16x16x32_bf16 v[56:59], v[154:157], v[166:169], v[56:59]
	v_mfma_f32_16x16x32_bf16 v[44:47], v[146:149], v[174:177], v[44:47]
	v_mfma_f32_16x16x32_bf16 v[40:43], v[154:157], v[174:177], v[40:43]
	v_mfma_f32_16x16x32_bf16 v[28:31], v[146:149], v[182:185], v[28:31]
	v_mfma_f32_16x16x32_bf16 v[24:27], v[154:157], v[182:185], v[24:27]
	v_mfma_f32_16x16x32_bf16 v[12:15], v[146:149], v[202:205], v[12:15]
	v_mfma_f32_16x16x32_bf16 v[8:11], v[154:157], v[202:205], v[8:11]
	s_setprio 0
	s_barrier
	s_add_u32 s10, s10, 0xc000
	s_addc_u32 s11, s11, 0
	s_add_i32 s14, s35, s6
	v_lshl_add_u64 v[142:143], s[10:11], 0, v[134:135]
	s_mov_b32 m0, s14
	s_nop 0
	global_load_lds_dwordx4 v[142:143], off
	v_lshl_add_u64 v[142:143], s[10:11], 0, v[130:131]
	s_add_i32 m0, s14, 0x2000
	s_nop 0
	global_load_lds_dwordx4 v[142:143], off
	s_waitcnt vmcnt(6)
	s_barrier
	s_setprio 1
	v_mfma_f32_16x16x32_bf16 v[52:55], v[206:209], v[158:161], v[52:55]
	v_mfma_f32_16x16x32_bf16 v[48:51], v[214:217], v[158:161], v[48:51]
	v_mfma_f32_16x16x32_bf16 v[36:39], v[206:209], v[170:173], v[36:39]
	v_mfma_f32_16x16x32_bf16 v[32:35], v[214:217], v[170:173], v[32:35]
	v_mfma_f32_16x16x32_bf16 v[20:23], v[206:209], v[178:181], v[20:23]
	v_mfma_f32_16x16x32_bf16 v[16:19], v[214:217], v[178:181], v[16:19]
	v_mfma_f32_16x16x32_bf16 v[4:7], v[206:209], v[198:201], v[4:7]
	v_mfma_f32_16x16x32_bf16 v[0:3], v[214:217], v[198:201], v[0:3]
	v_mfma_f32_16x16x32_bf16 v[52:55], v[210:213], v[166:169], v[52:55]
	v_mfma_f32_16x16x32_bf16 v[48:51], v[218:221], v[166:169], v[48:51]
	v_mfma_f32_16x16x32_bf16 v[36:39], v[210:213], v[174:177], v[36:39]
	v_mfma_f32_16x16x32_bf16 v[32:35], v[218:221], v[174:177], v[32:35]
	v_mfma_f32_16x16x32_bf16 v[20:23], v[210:213], v[182:185], v[20:23]
	v_mfma_f32_16x16x32_bf16 v[16:19], v[218:221], v[182:185], v[16:19]
	v_mfma_f32_16x16x32_bf16 v[4:7], v[210:213], v[202:205], v[4:7]
	v_mfma_f32_16x16x32_bf16 v[0:3], v[218:221], v[202:205], v[0:3]
	s_setprio 0
	s_add_i32 s53, s53, 2
	s_add_u32 s51, s51, 0x10000
	s_addc_u32 s52, s52, 0
	s_add_u32 s8, s8, 0x100
	s_addc_u32 s9, s9, 0
	s_cmp_gt_u32 s53, 13
	s_barrier
	s_cbranch_scc0 .LBB0_893
	v_mov_b32_e32 v142, v188
	s_lshl_b32 s1, s1, 8
	v_readfirstlane_b32 s5, v142
	s_lshr_b32 s8, s5, 2
	s_and_b32 s8, s8, 0x3fffc0
	s_add_i32 s8, s8, s1
	v_and_or_b32 v143, v142, 15, s8
	s_lshl_b32 s0, s0, 8
	s_lshr_b32 s1, s5, 1
	v_lshrrev_b32_e32 v142, 2, v142
	s_and_b32 s1, s1, 0x60
	v_and_or_b32 v142, v142, 12, s0
	v_or_b32_e32 v142, s1, v142
	v_lshl_add_u32 v164, v143, 10, v142
	v_mov_b32_e32 v240, 0x3d372713
	v_mov_b32_e32 v241, 0x3d372713
	v_mov_b32_e32 v242, 0xc0135761
	v_mov_b32_e32 v243, 0xc0135761
	v_mov_b32_e32 v244, 1.0
	v_mov_b32_e32 v245, 1.0
	v_pk_mul_f32 v[246:247], v[240:241], v[124:125]
	v_pk_mul_f32 v[248:249], v[240:241], v[126:127]
	v_pk_fma_f32 v[246:247], v[124:125], v[246:247], v[244:245]
	v_pk_fma_f32 v[248:249], v[126:127], v[248:249], v[244:245]
	v_pk_mul_f32 v[246:247], v[124:125], v[246:247]
	v_pk_mul_f32 v[248:249], v[126:127], v[248:249]
	v_pk_mul_f32 v[246:247], v[242:243], v[246:247]
	v_pk_mul_f32 v[248:249], v[242:243], v[248:249]
	v_exp_f32_e32 v246, v246
	v_exp_f32_e32 v247, v247
	v_exp_f32_e32 v248, v248
	v_exp_f32_e32 v249, v249
	v_pk_add_f32 v[246:247], v[246:247], v[244:245]
	v_pk_add_f32 v[248:249], v[248:249], v[244:245]
	v_rcp_f32_e32 v246, v246
	v_rcp_f32_e32 v247, v247
	v_rcp_f32_e32 v248, v248
	v_rcp_f32_e32 v249, v249
	v_pk_mul_f32 v[124:125], v[124:125], v[246:247]
	v_pk_mul_f32 v[126:127], v[126:127], v[248:249]
	s_and_b64 vcc, exec, s[20:21]
	s_mov_b32 s1, s4
	s_mov_b32 s0, s33
	s_mov_b64 s[8:9], s[30:31]
	s_mov_b64 s[10:11], s[12:13]
	s_nop 0
	s_nop 0
	v_cvt_pk_bf16_f32 v124, v124, v125
	s_nop 0
	s_nop 0
	s_nop 0
	s_nop 0
	v_cvt_pk_bf16_f32 v125, v126, v127
	v_lshl_add_u64 v[126:127], v[164:165], 1, s[36:37]
	global_store_dwordx2 v[126:127], v[124:125], off
	v_pk_mul_f32 v[246:247], v[240:241], v[120:121]
	v_pk_mul_f32 v[248:249], v[240:241], v[122:123]
	v_pk_fma_f32 v[246:247], v[120:121], v[246:247], v[244:245]
	v_pk_fma_f32 v[248:249], v[122:123], v[248:249], v[244:245]
	v_pk_mul_f32 v[246:247], v[120:121], v[246:247]
	v_pk_mul_f32 v[248:249], v[122:123], v[248:249]
	v_pk_mul_f32 v[246:247], v[242:243], v[246:247]
	v_pk_mul_f32 v[248:249], v[242:243], v[248:249]
	v_exp_f32_e32 v246, v246
	v_exp_f32_e32 v247, v247
	v_exp_f32_e32 v248, v248
	v_exp_f32_e32 v249, v249
	v_pk_add_f32 v[246:247], v[246:247], v[244:245]
	v_pk_add_f32 v[248:249], v[248:249], v[244:245]
	v_rcp_f32_e32 v246, v246
	v_rcp_f32_e32 v247, v247
	v_rcp_f32_e32 v248, v248
	v_rcp_f32_e32 v249, v249
	v_pk_mul_f32 v[120:121], v[120:121], v[246:247]
	v_pk_mul_f32 v[122:123], v[122:123], v[248:249]
	s_nop 0
	s_nop 0
	s_nop 0
	s_nop 0
	v_cvt_pk_bf16_f32 v120, v120, v121
	s_nop 0
	s_nop 0
	s_nop 0
	s_nop 0
	v_cvt_pk_bf16_f32 v121, v122, v123
	v_or_b32_e32 v122, 16, v164
	v_mov_b32_e32 v123, v165
	v_lshl_add_u64 v[122:123], v[122:123], 1, s[36:37]
	global_store_dwordx2 v[122:123], v[120:121], off
	v_pk_mul_f32 v[246:247], v[240:241], v[116:117]
	v_pk_mul_f32 v[248:249], v[240:241], v[118:119]
	v_pk_fma_f32 v[246:247], v[116:117], v[246:247], v[244:245]
	v_pk_fma_f32 v[248:249], v[118:119], v[248:249], v[244:245]
	v_pk_mul_f32 v[246:247], v[116:117], v[246:247]
	v_pk_mul_f32 v[248:249], v[118:119], v[248:249]
	v_pk_mul_f32 v[246:247], v[242:243], v[246:247]
	v_pk_mul_f32 v[248:249], v[242:243], v[248:249]
	v_exp_f32_e32 v246, v246
	v_exp_f32_e32 v247, v247
	v_exp_f32_e32 v248, v248
	v_exp_f32_e32 v249, v249
	v_pk_add_f32 v[246:247], v[246:247], v[244:245]
	v_pk_add_f32 v[248:249], v[248:249], v[244:245]
	v_rcp_f32_e32 v246, v246
	v_rcp_f32_e32 v247, v247
	v_rcp_f32_e32 v248, v248
	v_rcp_f32_e32 v249, v249
	v_pk_mul_f32 v[116:117], v[116:117], v[246:247]
	v_pk_mul_f32 v[118:119], v[118:119], v[248:249]
	v_or_b32_e32 v120, 0x80, v164
	s_nop 0
	s_nop 0
	s_nop 0
	v_cvt_pk_bf16_f32 v116, v116, v117
	s_nop 0
	s_nop 0
	s_nop 0
	s_nop 0
	v_mov_b32_e32 v121, v165
	v_cvt_pk_bf16_f32 v117, v118, v119
	v_lshl_add_u64 v[118:119], v[120:121], 1, s[36:37]
	global_store_dwordx2 v[118:119], v[116:117], off
	v_pk_mul_f32 v[246:247], v[240:241], v[112:113]
	v_pk_mul_f32 v[248:249], v[240:241], v[114:115]
	v_pk_fma_f32 v[246:247], v[112:113], v[246:247], v[244:245]
	v_pk_fma_f32 v[248:249], v[114:115], v[248:249], v[244:245]
	v_pk_mul_f32 v[246:247], v[112:113], v[246:247]
	v_pk_mul_f32 v[248:249], v[114:115], v[248:249]
	v_pk_mul_f32 v[246:247], v[242:243], v[246:247]
	v_pk_mul_f32 v[248:249], v[242:243], v[248:249]
	v_exp_f32_e32 v246, v246
	v_exp_f32_e32 v247, v247
	v_exp_f32_e32 v248, v248
	v_exp_f32_e32 v249, v249
	v_pk_add_f32 v[246:247], v[246:247], v[244:245]
	v_pk_add_f32 v[248:249], v[248:249], v[244:245]
	v_rcp_f32_e32 v246, v246
	v_rcp_f32_e32 v247, v247
	v_rcp_f32_e32 v248, v248
	v_rcp_f32_e32 v249, v249
	v_pk_mul_f32 v[112:113], v[112:113], v[246:247]
	v_pk_mul_f32 v[114:115], v[114:115], v[248:249]
	s_nop 0
	s_nop 0
	s_nop 0
	s_nop 0
	v_cvt_pk_bf16_f32 v112, v112, v113
	s_nop 0
	s_nop 0
	s_nop 0
	s_nop 0
	v_cvt_pk_bf16_f32 v113, v114, v115
	v_or_b32_e32 v114, 0x90, v164
	v_mov_b32_e32 v115, v165
	v_lshl_add_u64 v[114:115], v[114:115], 1, s[36:37]
	global_store_dwordx2 v[114:115], v[112:113], off
	v_pk_mul_f32 v[246:247], v[240:241], v[108:109]
	v_pk_mul_f32 v[248:249], v[240:241], v[110:111]
	v_pk_fma_f32 v[246:247], v[108:109], v[246:247], v[244:245]
	v_pk_fma_f32 v[248:249], v[110:111], v[248:249], v[244:245]
	v_pk_mul_f32 v[246:247], v[108:109], v[246:247]
	v_pk_mul_f32 v[248:249], v[110:111], v[248:249]
	v_pk_mul_f32 v[246:247], v[242:243], v[246:247]
	v_pk_mul_f32 v[248:249], v[242:243], v[248:249]
	v_exp_f32_e32 v246, v246
	v_exp_f32_e32 v247, v247
	v_exp_f32_e32 v248, v248
	v_exp_f32_e32 v249, v249
	v_pk_add_f32 v[246:247], v[246:247], v[244:245]
	v_pk_add_f32 v[248:249], v[248:249], v[244:245]
	v_rcp_f32_e32 v246, v246
	v_rcp_f32_e32 v247, v247
	v_rcp_f32_e32 v248, v248
	v_rcp_f32_e32 v249, v249
	v_pk_mul_f32 v[108:109], v[108:109], v[246:247]
	v_pk_mul_f32 v[110:111], v[110:111], v[248:249]
	v_add_u32_e32 v112, 0x4000, v164
	s_nop 0
	s_nop 0
	s_nop 0
	v_cvt_pk_bf16_f32 v108, v108, v109
	s_nop 0
	s_nop 0
	s_nop 0
	s_nop 0
	v_mov_b32_e32 v113, v165
	v_cvt_pk_bf16_f32 v109, v110, v111
	v_lshl_add_u64 v[110:111], v[112:113], 1, s[36:37]
	global_store_dwordx2 v[110:111], v[108:109], off
	v_pk_mul_f32 v[246:247], v[240:241], v[104:105]
	v_pk_mul_f32 v[248:249], v[240:241], v[106:107]
	v_pk_fma_f32 v[246:247], v[104:105], v[246:247], v[244:245]
	v_pk_fma_f32 v[248:249], v[106:107], v[248:249], v[244:245]
	v_pk_mul_f32 v[246:247], v[104:105], v[246:247]
	v_pk_mul_f32 v[248:249], v[106:107], v[248:249]
	v_pk_mul_f32 v[246:247], v[242:243], v[246:247]
	v_pk_mul_f32 v[248:249], v[242:243], v[248:249]
	v_exp_f32_e32 v246, v246
	v_exp_f32_e32 v247, v247
	v_exp_f32_e32 v248, v248
	v_exp_f32_e32 v249, v249
	v_pk_add_f32 v[246:247], v[246:247], v[244:245]
	v_pk_add_f32 v[248:249], v[248:249], v[244:245]
	v_rcp_f32_e32 v246, v246
	v_rcp_f32_e32 v247, v247
	v_rcp_f32_e32 v248, v248
	v_rcp_f32_e32 v249, v249
	v_pk_mul_f32 v[104:105], v[104:105], v[246:247]
	v_pk_mul_f32 v[106:107], v[106:107], v[248:249]
	s_nop 0
	s_nop 0
	s_nop 0
	s_nop 0
	v_cvt_pk_bf16_f32 v104, v104, v105
	s_nop 0
	s_nop 0
	s_nop 0
	s_nop 0
	v_cvt_pk_bf16_f32 v105, v106, v107
	v_add_u32_e32 v106, 0x4010, v164
	v_mov_b32_e32 v107, v165
	v_lshl_add_u64 v[106:107], v[106:107], 1, s[36:37]
	global_store_dwordx2 v[106:107], v[104:105], off
	v_pk_mul_f32 v[246:247], v[240:241], v[100:101]
	v_pk_mul_f32 v[248:249], v[240:241], v[102:103]
	v_pk_fma_f32 v[246:247], v[100:101], v[246:247], v[244:245]
	v_pk_fma_f32 v[248:249], v[102:103], v[248:249], v[244:245]
	v_pk_mul_f32 v[246:247], v[100:101], v[246:247]
	v_pk_mul_f32 v[248:249], v[102:103], v[248:249]
	v_pk_mul_f32 v[246:247], v[242:243], v[246:247]
	v_pk_mul_f32 v[248:249], v[242:243], v[248:249]
	v_exp_f32_e32 v246, v246
	v_exp_f32_e32 v247, v247
	v_exp_f32_e32 v248, v248
	v_exp_f32_e32 v249, v249
	v_pk_add_f32 v[246:247], v[246:247], v[244:245]
	v_pk_add_f32 v[248:249], v[248:249], v[244:245]
	v_rcp_f32_e32 v246, v246
	v_rcp_f32_e32 v247, v247
	v_rcp_f32_e32 v248, v248
	v_rcp_f32_e32 v249, v249
	v_pk_mul_f32 v[100:101], v[100:101], v[246:247]
	v_pk_mul_f32 v[102:103], v[102:103], v[248:249]
	v_add_u32_e32 v104, 0x4080, v164
	s_nop 0
	s_nop 0
	s_nop 0
	v_cvt_pk_bf16_f32 v100, v100, v101
	s_nop 0
	s_nop 0
	s_nop 0
	s_nop 0
	v_mov_b32_e32 v105, v165
	v_cvt_pk_bf16_f32 v101, v102, v103
	v_lshl_add_u64 v[102:103], v[104:105], 1, s[36:37]
	global_store_dwordx2 v[102:103], v[100:101], off
	v_pk_mul_f32 v[246:247], v[240:241], v[96:97]
	v_pk_mul_f32 v[248:249], v[240:241], v[98:99]
	v_pk_fma_f32 v[246:247], v[96:97], v[246:247], v[244:245]
	v_pk_fma_f32 v[248:249], v[98:99], v[248:249], v[244:245]
	v_pk_mul_f32 v[246:247], v[96:97], v[246:247]
	v_pk_mul_f32 v[248:249], v[98:99], v[248:249]
	v_pk_mul_f32 v[246:247], v[242:243], v[246:247]
	v_pk_mul_f32 v[248:249], v[242:243], v[248:249]
	v_exp_f32_e32 v246, v246
	v_exp_f32_e32 v247, v247
	v_exp_f32_e32 v248, v248
	v_exp_f32_e32 v249, v249
	v_pk_add_f32 v[246:247], v[246:247], v[244:245]
	v_pk_add_f32 v[248:249], v[248:249], v[244:245]
	v_rcp_f32_e32 v246, v246
	v_rcp_f32_e32 v247, v247
	v_rcp_f32_e32 v248, v248
	v_rcp_f32_e32 v249, v249
	v_pk_mul_f32 v[96:97], v[96:97], v[246:247]
	v_pk_mul_f32 v[98:99], v[98:99], v[248:249]
	s_nop 0
	s_nop 0
	s_nop 0
	s_nop 0
	v_cvt_pk_bf16_f32 v96, v96, v97
	s_nop 0
	s_nop 0
	s_nop 0
	s_nop 0
	v_cvt_pk_bf16_f32 v97, v98, v99
	v_add_u32_e32 v98, 0x4090, v164
	v_mov_b32_e32 v99, v165
	v_lshl_add_u64 v[98:99], v[98:99], 1, s[36:37]
	global_store_dwordx2 v[98:99], v[96:97], off
	v_pk_mul_f32 v[246:247], v[240:241], v[92:93]
	v_pk_mul_f32 v[248:249], v[240:241], v[94:95]
	v_pk_fma_f32 v[246:247], v[92:93], v[246:247], v[244:245]
	v_pk_fma_f32 v[248:249], v[94:95], v[248:249], v[244:245]
	v_pk_mul_f32 v[246:247], v[92:93], v[246:247]
	v_pk_mul_f32 v[248:249], v[94:95], v[248:249]
	v_pk_mul_f32 v[246:247], v[242:243], v[246:247]
	v_pk_mul_f32 v[248:249], v[242:243], v[248:249]
	v_exp_f32_e32 v246, v246
	v_exp_f32_e32 v247, v247
	v_exp_f32_e32 v248, v248
	v_exp_f32_e32 v249, v249
	v_pk_add_f32 v[246:247], v[246:247], v[244:245]
	v_pk_add_f32 v[248:249], v[248:249], v[244:245]
	v_rcp_f32_e32 v246, v246
	v_rcp_f32_e32 v247, v247
	v_rcp_f32_e32 v248, v248
	v_rcp_f32_e32 v249, v249
	v_pk_mul_f32 v[92:93], v[92:93], v[246:247]
	v_pk_mul_f32 v[94:95], v[94:95], v[248:249]
	v_add_u32_e32 v96, 0x8000, v164
	s_nop 0
	s_nop 0
	s_nop 0
	v_cvt_pk_bf16_f32 v92, v92, v93
	s_nop 0
	s_nop 0
	s_nop 0
	s_nop 0
	v_mov_b32_e32 v97, v165
	v_cvt_pk_bf16_f32 v93, v94, v95
	v_lshl_add_u64 v[94:95], v[96:97], 1, s[36:37]
	global_store_dwordx2 v[94:95], v[92:93], off
	v_pk_mul_f32 v[246:247], v[240:241], v[88:89]
	v_pk_mul_f32 v[248:249], v[240:241], v[90:91]
	v_pk_fma_f32 v[246:247], v[88:89], v[246:247], v[244:245]
	v_pk_fma_f32 v[248:249], v[90:91], v[248:249], v[244:245]
	v_pk_mul_f32 v[246:247], v[88:89], v[246:247]
	v_pk_mul_f32 v[248:249], v[90:91], v[248:249]
	v_pk_mul_f32 v[246:247], v[242:243], v[246:247]
	v_pk_mul_f32 v[248:249], v[242:243], v[248:249]
	v_exp_f32_e32 v246, v246
	v_exp_f32_e32 v247, v247
	v_exp_f32_e32 v248, v248
	v_exp_f32_e32 v249, v249
	v_pk_add_f32 v[246:247], v[246:247], v[244:245]
	v_pk_add_f32 v[248:249], v[248:249], v[244:245]
	v_rcp_f32_e32 v246, v246
	v_rcp_f32_e32 v247, v247
	v_rcp_f32_e32 v248, v248
	v_rcp_f32_e32 v249, v249
	v_pk_mul_f32 v[88:89], v[88:89], v[246:247]
	v_pk_mul_f32 v[90:91], v[90:91], v[248:249]
	s_nop 0
	s_nop 0
	s_nop 0
	s_nop 0
	v_cvt_pk_bf16_f32 v88, v88, v89
	s_nop 0
	s_nop 0
	s_nop 0
	s_nop 0
	v_cvt_pk_bf16_f32 v89, v90, v91
	v_add_u32_e32 v90, 0x8010, v164
	v_mov_b32_e32 v91, v165
	v_lshl_add_u64 v[90:91], v[90:91], 1, s[36:37]
	global_store_dwordx2 v[90:91], v[88:89], off
	v_pk_mul_f32 v[246:247], v[240:241], v[84:85]
	v_pk_mul_f32 v[248:249], v[240:241], v[86:87]
	v_pk_fma_f32 v[246:247], v[84:85], v[246:247], v[244:245]
	v_pk_fma_f32 v[248:249], v[86:87], v[248:249], v[244:245]
	v_pk_mul_f32 v[246:247], v[84:85], v[246:247]
	v_pk_mul_f32 v[248:249], v[86:87], v[248:249]
	v_pk_mul_f32 v[246:247], v[242:243], v[246:247]
	v_pk_mul_f32 v[248:249], v[242:243], v[248:249]
	v_exp_f32_e32 v246, v246
	v_exp_f32_e32 v247, v247
	v_exp_f32_e32 v248, v248
	v_exp_f32_e32 v249, v249
	v_pk_add_f32 v[246:247], v[246:247], v[244:245]
	v_pk_add_f32 v[248:249], v[248:249], v[244:245]
	v_rcp_f32_e32 v246, v246
	v_rcp_f32_e32 v247, v247
	v_rcp_f32_e32 v248, v248
	v_rcp_f32_e32 v249, v249
	v_pk_mul_f32 v[84:85], v[84:85], v[246:247]
	v_pk_mul_f32 v[86:87], v[86:87], v[248:249]
	v_add_u32_e32 v88, 0x8080, v164
	s_nop 0
	s_nop 0
	s_nop 0
	v_cvt_pk_bf16_f32 v84, v84, v85
	s_nop 0
	s_nop 0
	s_nop 0
	s_nop 0
	v_mov_b32_e32 v89, v165
	v_cvt_pk_bf16_f32 v85, v86, v87
	v_lshl_add_u64 v[86:87], v[88:89], 1, s[36:37]
	global_store_dwordx2 v[86:87], v[84:85], off
	v_pk_mul_f32 v[246:247], v[240:241], v[80:81]
	v_pk_mul_f32 v[248:249], v[240:241], v[82:83]
	v_pk_fma_f32 v[246:247], v[80:81], v[246:247], v[244:245]
	v_pk_fma_f32 v[248:249], v[82:83], v[248:249], v[244:245]
	v_pk_mul_f32 v[246:247], v[80:81], v[246:247]
	v_pk_mul_f32 v[248:249], v[82:83], v[248:249]
	v_pk_mul_f32 v[246:247], v[242:243], v[246:247]
	v_pk_mul_f32 v[248:249], v[242:243], v[248:249]
	v_exp_f32_e32 v246, v246
	v_exp_f32_e32 v247, v247
	v_exp_f32_e32 v248, v248
	v_exp_f32_e32 v249, v249
	v_pk_add_f32 v[246:247], v[246:247], v[244:245]
	v_pk_add_f32 v[248:249], v[248:249], v[244:245]
	v_rcp_f32_e32 v246, v246
	v_rcp_f32_e32 v247, v247
	v_rcp_f32_e32 v248, v248
	v_rcp_f32_e32 v249, v249
	v_pk_mul_f32 v[80:81], v[80:81], v[246:247]
	v_pk_mul_f32 v[82:83], v[82:83], v[248:249]
	s_nop 0
	s_nop 0
	s_nop 0
	s_nop 0
	v_cvt_pk_bf16_f32 v80, v80, v81
	s_nop 0
	s_nop 0
	s_nop 0
	s_nop 0
	v_cvt_pk_bf16_f32 v81, v82, v83
	v_add_u32_e32 v82, 0x8090, v164
	v_mov_b32_e32 v83, v165
	v_lshl_add_u64 v[82:83], v[82:83], 1, s[36:37]
	global_store_dwordx2 v[82:83], v[80:81], off
	v_pk_mul_f32 v[246:247], v[240:241], v[76:77]
	v_pk_mul_f32 v[248:249], v[240:241], v[78:79]
	v_pk_fma_f32 v[246:247], v[76:77], v[246:247], v[244:245]
	v_pk_fma_f32 v[248:249], v[78:79], v[248:249], v[244:245]
	v_pk_mul_f32 v[246:247], v[76:77], v[246:247]
	v_pk_mul_f32 v[248:249], v[78:79], v[248:249]
	v_pk_mul_f32 v[246:247], v[242:243], v[246:247]
	v_pk_mul_f32 v[248:249], v[242:243], v[248:249]
	v_exp_f32_e32 v246, v246
	v_exp_f32_e32 v247, v247
	v_exp_f32_e32 v248, v248
	v_exp_f32_e32 v249, v249
	v_pk_add_f32 v[246:247], v[246:247], v[244:245]
	v_pk_add_f32 v[248:249], v[248:249], v[244:245]
	v_rcp_f32_e32 v246, v246
	v_rcp_f32_e32 v247, v247
	v_rcp_f32_e32 v248, v248
	v_rcp_f32_e32 v249, v249
	v_pk_mul_f32 v[76:77], v[76:77], v[246:247]
	v_pk_mul_f32 v[78:79], v[78:79], v[248:249]
	v_add_u32_e32 v80, 0xc000, v164
	s_nop 0
	s_nop 0
	s_nop 0
	v_cvt_pk_bf16_f32 v76, v76, v77
	s_nop 0
	s_nop 0
	s_nop 0
	s_nop 0
	v_mov_b32_e32 v81, v165
	v_cvt_pk_bf16_f32 v77, v78, v79
	v_lshl_add_u64 v[78:79], v[80:81], 1, s[36:37]
	global_store_dwordx2 v[78:79], v[76:77], off
	v_pk_mul_f32 v[246:247], v[240:241], v[72:73]
	v_pk_mul_f32 v[248:249], v[240:241], v[74:75]
	v_pk_fma_f32 v[246:247], v[72:73], v[246:247], v[244:245]
	v_pk_fma_f32 v[248:249], v[74:75], v[248:249], v[244:245]
	v_pk_mul_f32 v[246:247], v[72:73], v[246:247]
	v_pk_mul_f32 v[248:249], v[74:75], v[248:249]
	v_pk_mul_f32 v[246:247], v[242:243], v[246:247]
	v_pk_mul_f32 v[248:249], v[242:243], v[248:249]
	v_exp_f32_e32 v246, v246
	v_exp_f32_e32 v247, v247
	v_exp_f32_e32 v248, v248
	v_exp_f32_e32 v249, v249
	v_pk_add_f32 v[246:247], v[246:247], v[244:245]
	v_pk_add_f32 v[248:249], v[248:249], v[244:245]
	v_rcp_f32_e32 v246, v246
	v_rcp_f32_e32 v247, v247
	v_rcp_f32_e32 v248, v248
	v_rcp_f32_e32 v249, v249
	v_pk_mul_f32 v[72:73], v[72:73], v[246:247]
	v_pk_mul_f32 v[74:75], v[74:75], v[248:249]
	s_nop 0
	s_nop 0
	s_nop 0
	s_nop 0
	v_cvt_pk_bf16_f32 v72, v72, v73
	s_nop 0
	s_nop 0
	s_nop 0
	s_nop 0
	v_cvt_pk_bf16_f32 v73, v74, v75
	v_add_u32_e32 v74, 0xc010, v164
	v_mov_b32_e32 v75, v165
	v_lshl_add_u64 v[74:75], v[74:75], 1, s[36:37]
	global_store_dwordx2 v[74:75], v[72:73], off
	v_pk_mul_f32 v[246:247], v[240:241], v[68:69]
	v_pk_mul_f32 v[248:249], v[240:241], v[70:71]
	v_pk_fma_f32 v[246:247], v[68:69], v[246:247], v[244:245]
	v_pk_fma_f32 v[248:249], v[70:71], v[248:249], v[244:245]
	v_pk_mul_f32 v[246:247], v[68:69], v[246:247]
	v_pk_mul_f32 v[248:249], v[70:71], v[248:249]
	v_pk_mul_f32 v[246:247], v[242:243], v[246:247]
	v_pk_mul_f32 v[248:249], v[242:243], v[248:249]
	v_exp_f32_e32 v246, v246
	v_exp_f32_e32 v247, v247
	v_exp_f32_e32 v248, v248
	v_exp_f32_e32 v249, v249
	v_pk_add_f32 v[246:247], v[246:247], v[244:245]
	v_pk_add_f32 v[248:249], v[248:249], v[244:245]
	v_rcp_f32_e32 v246, v246
	v_rcp_f32_e32 v247, v247
	v_rcp_f32_e32 v248, v248
	v_rcp_f32_e32 v249, v249
	v_pk_mul_f32 v[68:69], v[68:69], v[246:247]
	v_pk_mul_f32 v[70:71], v[70:71], v[248:249]
	v_add_u32_e32 v72, 0xc080, v164
	s_nop 0
	s_nop 0
	s_nop 0
	v_cvt_pk_bf16_f32 v68, v68, v69
	s_nop 0
	s_nop 0
	s_nop 0
	s_nop 0
	v_mov_b32_e32 v73, v165
	v_cvt_pk_bf16_f32 v69, v70, v71
	v_lshl_add_u64 v[70:71], v[72:73], 1, s[36:37]
	global_store_dwordx2 v[70:71], v[68:69], off
	v_pk_mul_f32 v[246:247], v[240:241], v[64:65]
	v_pk_mul_f32 v[248:249], v[240:241], v[66:67]
	v_pk_fma_f32 v[246:247], v[64:65], v[246:247], v[244:245]
	v_pk_fma_f32 v[248:249], v[66:67], v[248:249], v[244:245]
	v_pk_mul_f32 v[246:247], v[64:65], v[246:247]
	v_pk_mul_f32 v[248:249], v[66:67], v[248:249]
	v_pk_mul_f32 v[246:247], v[242:243], v[246:247]
	v_pk_mul_f32 v[248:249], v[242:243], v[248:249]
	v_exp_f32_e32 v246, v246
	v_exp_f32_e32 v247, v247
	v_exp_f32_e32 v248, v248
	v_exp_f32_e32 v249, v249
	v_pk_add_f32 v[246:247], v[246:247], v[244:245]
	v_pk_add_f32 v[248:249], v[248:249], v[244:245]
	v_rcp_f32_e32 v246, v246
	v_rcp_f32_e32 v247, v247
	v_rcp_f32_e32 v248, v248
	v_rcp_f32_e32 v249, v249
	v_pk_mul_f32 v[64:65], v[64:65], v[246:247]
	v_pk_mul_f32 v[66:67], v[66:67], v[248:249]
	s_nop 0
	s_nop 0
	s_nop 0
	s_nop 0
	v_cvt_pk_bf16_f32 v64, v64, v65
	s_nop 0
	s_nop 0
	s_nop 0
	s_nop 0
	v_cvt_pk_bf16_f32 v65, v66, v67
	v_add_u32_e32 v66, 0xc090, v164
	v_mov_b32_e32 v67, v165
	v_lshl_add_u64 v[66:67], v[66:67], 1, s[36:37]
	global_store_dwordx2 v[66:67], v[64:65], off
	v_pk_mul_f32 v[246:247], v[240:241], v[60:61]
	v_pk_mul_f32 v[248:249], v[240:241], v[62:63]
	v_pk_fma_f32 v[246:247], v[60:61], v[246:247], v[244:245]
	v_pk_fma_f32 v[248:249], v[62:63], v[248:249], v[244:245]
	v_pk_mul_f32 v[246:247], v[60:61], v[246:247]
	v_pk_mul_f32 v[248:249], v[62:63], v[248:249]
	v_pk_mul_f32 v[246:247], v[242:243], v[246:247]
	v_pk_mul_f32 v[248:249], v[242:243], v[248:249]
	v_exp_f32_e32 v246, v246
	v_exp_f32_e32 v247, v247
	v_exp_f32_e32 v248, v248
	v_exp_f32_e32 v249, v249
	v_pk_add_f32 v[246:247], v[246:247], v[244:245]
	v_pk_add_f32 v[248:249], v[248:249], v[244:245]
	v_rcp_f32_e32 v246, v246
	v_rcp_f32_e32 v247, v247
	v_rcp_f32_e32 v248, v248
	v_rcp_f32_e32 v249, v249
	v_pk_mul_f32 v[60:61], v[60:61], v[246:247]
	v_pk_mul_f32 v[62:63], v[62:63], v[248:249]
	v_add_u32_e32 v64, 0x20000, v164
	s_nop 0
	s_nop 0
	s_nop 0
	v_cvt_pk_bf16_f32 v60, v60, v61
	s_nop 0
	s_nop 0
	s_nop 0
	s_nop 0
	v_mov_b32_e32 v65, v165
	v_cvt_pk_bf16_f32 v61, v62, v63
	v_lshl_add_u64 v[62:63], v[64:65], 1, s[36:37]
	global_store_dwordx2 v[62:63], v[60:61], off
	v_pk_mul_f32 v[246:247], v[240:241], v[56:57]
	v_pk_mul_f32 v[248:249], v[240:241], v[58:59]
	v_pk_fma_f32 v[246:247], v[56:57], v[246:247], v[244:245]
	v_pk_fma_f32 v[248:249], v[58:59], v[248:249], v[244:245]
	v_pk_mul_f32 v[246:247], v[56:57], v[246:247]
	v_pk_mul_f32 v[248:249], v[58:59], v[248:249]
	v_pk_mul_f32 v[246:247], v[242:243], v[246:247]
	v_pk_mul_f32 v[248:249], v[242:243], v[248:249]
	v_exp_f32_e32 v246, v246
	v_exp_f32_e32 v247, v247
	v_exp_f32_e32 v248, v248
	v_exp_f32_e32 v249, v249
	v_pk_add_f32 v[246:247], v[246:247], v[244:245]
	v_pk_add_f32 v[248:249], v[248:249], v[244:245]
	v_rcp_f32_e32 v246, v246
	v_rcp_f32_e32 v247, v247
	v_rcp_f32_e32 v248, v248
	v_rcp_f32_e32 v249, v249
	v_pk_mul_f32 v[56:57], v[56:57], v[246:247]
	v_pk_mul_f32 v[58:59], v[58:59], v[248:249]
	s_nop 0
	s_nop 0
	s_nop 0
	s_nop 0
	v_cvt_pk_bf16_f32 v56, v56, v57
	s_nop 0
	s_nop 0
	s_nop 0
	s_nop 0
	v_cvt_pk_bf16_f32 v57, v58, v59
	v_add_u32_e32 v58, 0x20010, v164
	v_mov_b32_e32 v59, v165
	v_lshl_add_u64 v[58:59], v[58:59], 1, s[36:37]
	global_store_dwordx2 v[58:59], v[56:57], off
	v_pk_mul_f32 v[246:247], v[240:241], v[52:53]
	v_pk_mul_f32 v[248:249], v[240:241], v[54:55]
	v_pk_fma_f32 v[246:247], v[52:53], v[246:247], v[244:245]
	v_pk_fma_f32 v[248:249], v[54:55], v[248:249], v[244:245]
	v_pk_mul_f32 v[246:247], v[52:53], v[246:247]
	v_pk_mul_f32 v[248:249], v[54:55], v[248:249]
	v_pk_mul_f32 v[246:247], v[242:243], v[246:247]
	v_pk_mul_f32 v[248:249], v[242:243], v[248:249]
	v_exp_f32_e32 v246, v246
	v_exp_f32_e32 v247, v247
	v_exp_f32_e32 v248, v248
	v_exp_f32_e32 v249, v249
	v_pk_add_f32 v[246:247], v[246:247], v[244:245]
	v_pk_add_f32 v[248:249], v[248:249], v[244:245]
	v_rcp_f32_e32 v246, v246
	v_rcp_f32_e32 v247, v247
	v_rcp_f32_e32 v248, v248
	v_rcp_f32_e32 v249, v249
	v_pk_mul_f32 v[52:53], v[52:53], v[246:247]
	v_pk_mul_f32 v[54:55], v[54:55], v[248:249]
	v_add_u32_e32 v56, 0x20080, v164
	s_nop 0
	s_nop 0
	s_nop 0
	v_cvt_pk_bf16_f32 v52, v52, v53
	s_nop 0
	s_nop 0
	s_nop 0
	s_nop 0
	v_mov_b32_e32 v57, v165
	v_cvt_pk_bf16_f32 v53, v54, v55
	v_lshl_add_u64 v[54:55], v[56:57], 1, s[36:37]
	global_store_dwordx2 v[54:55], v[52:53], off
	v_pk_mul_f32 v[246:247], v[240:241], v[48:49]
	v_pk_mul_f32 v[248:249], v[240:241], v[50:51]
	v_pk_fma_f32 v[246:247], v[48:49], v[246:247], v[244:245]
	v_pk_fma_f32 v[248:249], v[50:51], v[248:249], v[244:245]
	v_pk_mul_f32 v[246:247], v[48:49], v[246:247]
	v_pk_mul_f32 v[248:249], v[50:51], v[248:249]
	v_pk_mul_f32 v[246:247], v[242:243], v[246:247]
	v_pk_mul_f32 v[248:249], v[242:243], v[248:249]
	v_exp_f32_e32 v246, v246
	v_exp_f32_e32 v247, v247
	v_exp_f32_e32 v248, v248
	v_exp_f32_e32 v249, v249
	v_pk_add_f32 v[246:247], v[246:247], v[244:245]
	v_pk_add_f32 v[248:249], v[248:249], v[244:245]
	v_rcp_f32_e32 v246, v246
	v_rcp_f32_e32 v247, v247
	v_rcp_f32_e32 v248, v248
	v_rcp_f32_e32 v249, v249
	v_pk_mul_f32 v[48:49], v[48:49], v[246:247]
	v_pk_mul_f32 v[50:51], v[50:51], v[248:249]
	s_nop 0
	s_nop 0
	s_nop 0
	s_nop 0
	v_cvt_pk_bf16_f32 v48, v48, v49
	s_nop 0
	s_nop 0
	s_nop 0
	s_nop 0
	v_cvt_pk_bf16_f32 v49, v50, v51
	v_add_u32_e32 v50, 0x20090, v164
	v_mov_b32_e32 v51, v165
	v_lshl_add_u64 v[50:51], v[50:51], 1, s[36:37]
	global_store_dwordx2 v[50:51], v[48:49], off
	v_pk_mul_f32 v[246:247], v[240:241], v[44:45]
	v_pk_mul_f32 v[248:249], v[240:241], v[46:47]
	v_pk_fma_f32 v[246:247], v[44:45], v[246:247], v[244:245]
	v_pk_fma_f32 v[248:249], v[46:47], v[248:249], v[244:245]
	v_pk_mul_f32 v[246:247], v[44:45], v[246:247]
	v_pk_mul_f32 v[248:249], v[46:47], v[248:249]
	v_pk_mul_f32 v[246:247], v[242:243], v[246:247]
	v_pk_mul_f32 v[248:249], v[242:243], v[248:249]
	v_exp_f32_e32 v246, v246
	v_exp_f32_e32 v247, v247
	v_exp_f32_e32 v248, v248
	v_exp_f32_e32 v249, v249
	v_pk_add_f32 v[246:247], v[246:247], v[244:245]
	v_pk_add_f32 v[248:249], v[248:249], v[244:245]
	v_rcp_f32_e32 v246, v246
	v_rcp_f32_e32 v247, v247
	v_rcp_f32_e32 v248, v248
	v_rcp_f32_e32 v249, v249
	v_pk_mul_f32 v[44:45], v[44:45], v[246:247]
	v_pk_mul_f32 v[46:47], v[46:47], v[248:249]
	v_add_u32_e32 v48, 0x24000, v164
	s_nop 0
	s_nop 0
	s_nop 0
	v_cvt_pk_bf16_f32 v44, v44, v45
	s_nop 0
	s_nop 0
	s_nop 0
	s_nop 0
	v_mov_b32_e32 v49, v165
	v_cvt_pk_bf16_f32 v45, v46, v47
	v_lshl_add_u64 v[46:47], v[48:49], 1, s[36:37]
	global_store_dwordx2 v[46:47], v[44:45], off
	v_pk_mul_f32 v[246:247], v[240:241], v[40:41]
	v_pk_mul_f32 v[248:249], v[240:241], v[42:43]
	v_pk_fma_f32 v[246:247], v[40:41], v[246:247], v[244:245]
	v_pk_fma_f32 v[248:249], v[42:43], v[248:249], v[244:245]
	v_pk_mul_f32 v[246:247], v[40:41], v[246:247]
	v_pk_mul_f32 v[248:249], v[42:43], v[248:249]
	v_pk_mul_f32 v[246:247], v[242:243], v[246:247]
	v_pk_mul_f32 v[248:249], v[242:243], v[248:249]
	v_exp_f32_e32 v246, v246
	v_exp_f32_e32 v247, v247
	v_exp_f32_e32 v248, v248
	v_exp_f32_e32 v249, v249
	v_pk_add_f32 v[246:247], v[246:247], v[244:245]
	v_pk_add_f32 v[248:249], v[248:249], v[244:245]
	v_rcp_f32_e32 v246, v246
	v_rcp_f32_e32 v247, v247
	v_rcp_f32_e32 v248, v248
	v_rcp_f32_e32 v249, v249
	v_pk_mul_f32 v[40:41], v[40:41], v[246:247]
	v_pk_mul_f32 v[42:43], v[42:43], v[248:249]
	s_nop 0
	s_nop 0
	s_nop 0
	s_nop 0
	v_cvt_pk_bf16_f32 v40, v40, v41
	s_nop 0
	s_nop 0
	s_nop 0
	s_nop 0
	v_cvt_pk_bf16_f32 v41, v42, v43
	v_add_u32_e32 v42, 0x24010, v164
	v_mov_b32_e32 v43, v165
	v_lshl_add_u64 v[42:43], v[42:43], 1, s[36:37]
	global_store_dwordx2 v[42:43], v[40:41], off
	v_pk_mul_f32 v[246:247], v[240:241], v[36:37]
	v_pk_mul_f32 v[248:249], v[240:241], v[38:39]
	v_pk_fma_f32 v[246:247], v[36:37], v[246:247], v[244:245]
	v_pk_fma_f32 v[248:249], v[38:39], v[248:249], v[244:245]
	v_pk_mul_f32 v[246:247], v[36:37], v[246:247]
	v_pk_mul_f32 v[248:249], v[38:39], v[248:249]
	v_pk_mul_f32 v[246:247], v[242:243], v[246:247]
	v_pk_mul_f32 v[248:249], v[242:243], v[248:249]
	v_exp_f32_e32 v246, v246
	v_exp_f32_e32 v247, v247
	v_exp_f32_e32 v248, v248
	v_exp_f32_e32 v249, v249
	v_pk_add_f32 v[246:247], v[246:247], v[244:245]
	v_pk_add_f32 v[248:249], v[248:249], v[244:245]
	v_rcp_f32_e32 v246, v246
	v_rcp_f32_e32 v247, v247
	v_rcp_f32_e32 v248, v248
	v_rcp_f32_e32 v249, v249
	v_pk_mul_f32 v[36:37], v[36:37], v[246:247]
	v_pk_mul_f32 v[38:39], v[38:39], v[248:249]
	v_add_u32_e32 v40, 0x24080, v164
	s_nop 0
	s_nop 0
	s_nop 0
	v_cvt_pk_bf16_f32 v36, v36, v37
	s_nop 0
	s_nop 0
	s_nop 0
	s_nop 0
	v_mov_b32_e32 v41, v165
	v_cvt_pk_bf16_f32 v37, v38, v39
	v_lshl_add_u64 v[38:39], v[40:41], 1, s[36:37]
	global_store_dwordx2 v[38:39], v[36:37], off
	v_pk_mul_f32 v[246:247], v[240:241], v[32:33]
	v_pk_mul_f32 v[248:249], v[240:241], v[34:35]
	v_pk_fma_f32 v[246:247], v[32:33], v[246:247], v[244:245]
	v_pk_fma_f32 v[248:249], v[34:35], v[248:249], v[244:245]
	v_pk_mul_f32 v[246:247], v[32:33], v[246:247]
	v_pk_mul_f32 v[248:249], v[34:35], v[248:249]
	v_pk_mul_f32 v[246:247], v[242:243], v[246:247]
	v_pk_mul_f32 v[248:249], v[242:243], v[248:249]
	v_exp_f32_e32 v246, v246
	v_exp_f32_e32 v247, v247
	v_exp_f32_e32 v248, v248
	v_exp_f32_e32 v249, v249
	v_pk_add_f32 v[246:247], v[246:247], v[244:245]
	v_pk_add_f32 v[248:249], v[248:249], v[244:245]
	v_rcp_f32_e32 v246, v246
	v_rcp_f32_e32 v247, v247
	v_rcp_f32_e32 v248, v248
	v_rcp_f32_e32 v249, v249
	v_pk_mul_f32 v[32:33], v[32:33], v[246:247]
	v_pk_mul_f32 v[34:35], v[34:35], v[248:249]
	s_nop 0
	s_nop 0
	s_nop 0
	s_nop 0
	v_cvt_pk_bf16_f32 v32, v32, v33
	s_nop 0
	s_nop 0
	s_nop 0
	s_nop 0
	v_cvt_pk_bf16_f32 v33, v34, v35
	v_add_u32_e32 v34, 0x24090, v164
	v_mov_b32_e32 v35, v165
	v_lshl_add_u64 v[34:35], v[34:35], 1, s[36:37]
	global_store_dwordx2 v[34:35], v[32:33], off
	v_pk_mul_f32 v[246:247], v[240:241], v[28:29]
	v_pk_mul_f32 v[248:249], v[240:241], v[30:31]
	v_pk_fma_f32 v[246:247], v[28:29], v[246:247], v[244:245]
	v_pk_fma_f32 v[248:249], v[30:31], v[248:249], v[244:245]
	v_pk_mul_f32 v[246:247], v[28:29], v[246:247]
	v_pk_mul_f32 v[248:249], v[30:31], v[248:249]
	v_pk_mul_f32 v[246:247], v[242:243], v[246:247]
	v_pk_mul_f32 v[248:249], v[242:243], v[248:249]
	v_exp_f32_e32 v246, v246
	v_exp_f32_e32 v247, v247
	v_exp_f32_e32 v248, v248
	v_exp_f32_e32 v249, v249
	v_pk_add_f32 v[246:247], v[246:247], v[244:245]
	v_pk_add_f32 v[248:249], v[248:249], v[244:245]
	v_rcp_f32_e32 v246, v246
	v_rcp_f32_e32 v247, v247
	v_rcp_f32_e32 v248, v248
	v_rcp_f32_e32 v249, v249
	v_pk_mul_f32 v[28:29], v[28:29], v[246:247]
	v_pk_mul_f32 v[30:31], v[30:31], v[248:249]
	v_add_u32_e32 v32, 0x28000, v164
	s_nop 0
	s_nop 0
	s_nop 0
	v_cvt_pk_bf16_f32 v28, v28, v29
	s_nop 0
	s_nop 0
	s_nop 0
	s_nop 0
	v_mov_b32_e32 v33, v165
	v_cvt_pk_bf16_f32 v29, v30, v31
	v_lshl_add_u64 v[30:31], v[32:33], 1, s[36:37]
	global_store_dwordx2 v[30:31], v[28:29], off
	v_pk_mul_f32 v[246:247], v[240:241], v[24:25]
	v_pk_mul_f32 v[248:249], v[240:241], v[26:27]
	v_pk_fma_f32 v[246:247], v[24:25], v[246:247], v[244:245]
	v_pk_fma_f32 v[248:249], v[26:27], v[248:249], v[244:245]
	v_pk_mul_f32 v[246:247], v[24:25], v[246:247]
	v_pk_mul_f32 v[248:249], v[26:27], v[248:249]
	v_pk_mul_f32 v[246:247], v[242:243], v[246:247]
	v_pk_mul_f32 v[248:249], v[242:243], v[248:249]
	v_exp_f32_e32 v246, v246
	v_exp_f32_e32 v247, v247
	v_exp_f32_e32 v248, v248
	v_exp_f32_e32 v249, v249
	v_pk_add_f32 v[246:247], v[246:247], v[244:245]
	v_pk_add_f32 v[248:249], v[248:249], v[244:245]
	v_rcp_f32_e32 v246, v246
	v_rcp_f32_e32 v247, v247
	v_rcp_f32_e32 v248, v248
	v_rcp_f32_e32 v249, v249
	v_pk_mul_f32 v[24:25], v[24:25], v[246:247]
	v_pk_mul_f32 v[26:27], v[26:27], v[248:249]
	s_nop 0
	s_nop 0
	s_nop 0
	s_nop 0
	v_cvt_pk_bf16_f32 v24, v24, v25
	s_nop 0
	s_nop 0
	s_nop 0
	s_nop 0
	v_cvt_pk_bf16_f32 v25, v26, v27
	v_add_u32_e32 v26, 0x28010, v164
	v_mov_b32_e32 v27, v165
	v_lshl_add_u64 v[26:27], v[26:27], 1, s[36:37]
	global_store_dwordx2 v[26:27], v[24:25], off
	v_pk_mul_f32 v[246:247], v[240:241], v[20:21]
	v_pk_mul_f32 v[248:249], v[240:241], v[22:23]
	v_pk_fma_f32 v[246:247], v[20:21], v[246:247], v[244:245]
	v_pk_fma_f32 v[248:249], v[22:23], v[248:249], v[244:245]
	v_pk_mul_f32 v[246:247], v[20:21], v[246:247]
	v_pk_mul_f32 v[248:249], v[22:23], v[248:249]
	v_pk_mul_f32 v[246:247], v[242:243], v[246:247]
	v_pk_mul_f32 v[248:249], v[242:243], v[248:249]
	v_exp_f32_e32 v246, v246
	v_exp_f32_e32 v247, v247
	v_exp_f32_e32 v248, v248
	v_exp_f32_e32 v249, v249
	v_pk_add_f32 v[246:247], v[246:247], v[244:245]
	v_pk_add_f32 v[248:249], v[248:249], v[244:245]
	v_rcp_f32_e32 v246, v246
	v_rcp_f32_e32 v247, v247
	v_rcp_f32_e32 v248, v248
	v_rcp_f32_e32 v249, v249
	v_pk_mul_f32 v[20:21], v[20:21], v[246:247]
	v_pk_mul_f32 v[22:23], v[22:23], v[248:249]
	v_add_u32_e32 v24, 0x28080, v164
	s_nop 0
	s_nop 0
	s_nop 0
	v_cvt_pk_bf16_f32 v20, v20, v21
	s_nop 0
	s_nop 0
	s_nop 0
	s_nop 0
	v_mov_b32_e32 v25, v165
	v_cvt_pk_bf16_f32 v21, v22, v23
	v_lshl_add_u64 v[22:23], v[24:25], 1, s[36:37]
	global_store_dwordx2 v[22:23], v[20:21], off
	v_pk_mul_f32 v[246:247], v[240:241], v[16:17]
	v_pk_mul_f32 v[248:249], v[240:241], v[18:19]
	v_pk_fma_f32 v[246:247], v[16:17], v[246:247], v[244:245]
	v_pk_fma_f32 v[248:249], v[18:19], v[248:249], v[244:245]
	v_pk_mul_f32 v[246:247], v[16:17], v[246:247]
	v_pk_mul_f32 v[248:249], v[18:19], v[248:249]
	v_pk_mul_f32 v[246:247], v[242:243], v[246:247]
	v_pk_mul_f32 v[248:249], v[242:243], v[248:249]
	v_exp_f32_e32 v246, v246
	v_exp_f32_e32 v247, v247
	v_exp_f32_e32 v248, v248
	v_exp_f32_e32 v249, v249
	v_pk_add_f32 v[246:247], v[246:247], v[244:245]
	v_pk_add_f32 v[248:249], v[248:249], v[244:245]
	v_rcp_f32_e32 v246, v246
	v_rcp_f32_e32 v247, v247
	v_rcp_f32_e32 v248, v248
	v_rcp_f32_e32 v249, v249
	v_pk_mul_f32 v[16:17], v[16:17], v[246:247]
	v_pk_mul_f32 v[18:19], v[18:19], v[248:249]
	s_nop 0
	s_nop 0
	s_nop 0
	s_nop 0
	v_cvt_pk_bf16_f32 v16, v16, v17
	s_nop 0
	s_nop 0
	s_nop 0
	s_nop 0
	v_cvt_pk_bf16_f32 v17, v18, v19
	v_add_u32_e32 v18, 0x28090, v164
	v_mov_b32_e32 v19, v165
	v_lshl_add_u64 v[18:19], v[18:19], 1, s[36:37]
	global_store_dwordx2 v[18:19], v[16:17], off
	v_pk_mul_f32 v[246:247], v[240:241], v[12:13]
	v_pk_mul_f32 v[248:249], v[240:241], v[14:15]
	v_pk_fma_f32 v[246:247], v[12:13], v[246:247], v[244:245]
	v_pk_fma_f32 v[248:249], v[14:15], v[248:249], v[244:245]
	v_pk_mul_f32 v[246:247], v[12:13], v[246:247]
	v_pk_mul_f32 v[248:249], v[14:15], v[248:249]
	v_pk_mul_f32 v[246:247], v[242:243], v[246:247]
	v_pk_mul_f32 v[248:249], v[242:243], v[248:249]
	v_exp_f32_e32 v246, v246
	v_exp_f32_e32 v247, v247
	v_exp_f32_e32 v248, v248
	v_exp_f32_e32 v249, v249
	v_pk_add_f32 v[246:247], v[246:247], v[244:245]
	v_pk_add_f32 v[248:249], v[248:249], v[244:245]
	v_rcp_f32_e32 v246, v246
	v_rcp_f32_e32 v247, v247
	v_rcp_f32_e32 v248, v248
	v_rcp_f32_e32 v249, v249
	v_pk_mul_f32 v[12:13], v[12:13], v[246:247]
	v_pk_mul_f32 v[14:15], v[14:15], v[248:249]
	v_add_u32_e32 v16, 0x2c000, v164
	s_nop 0
	s_nop 0
	s_nop 0
	v_cvt_pk_bf16_f32 v12, v12, v13
	s_nop 0
	s_nop 0
	s_nop 0
	s_nop 0
	v_mov_b32_e32 v17, v165
	v_cvt_pk_bf16_f32 v13, v14, v15
	v_lshl_add_u64 v[14:15], v[16:17], 1, s[36:37]
	global_store_dwordx2 v[14:15], v[12:13], off
	v_pk_mul_f32 v[246:247], v[240:241], v[8:9]
	v_pk_mul_f32 v[248:249], v[240:241], v[10:11]
	v_pk_fma_f32 v[246:247], v[8:9], v[246:247], v[244:245]
	v_pk_fma_f32 v[248:249], v[10:11], v[248:249], v[244:245]
	v_pk_mul_f32 v[246:247], v[8:9], v[246:247]
	v_pk_mul_f32 v[248:249], v[10:11], v[248:249]
	v_pk_mul_f32 v[246:247], v[242:243], v[246:247]
	v_pk_mul_f32 v[248:249], v[242:243], v[248:249]
	v_exp_f32_e32 v246, v246
	v_exp_f32_e32 v247, v247
	v_exp_f32_e32 v248, v248
	v_exp_f32_e32 v249, v249
	v_pk_add_f32 v[246:247], v[246:247], v[244:245]
	v_pk_add_f32 v[248:249], v[248:249], v[244:245]
	v_rcp_f32_e32 v246, v246
	v_rcp_f32_e32 v247, v247
	v_rcp_f32_e32 v248, v248
	v_rcp_f32_e32 v249, v249
	v_pk_mul_f32 v[8:9], v[8:9], v[246:247]
	v_pk_mul_f32 v[10:11], v[10:11], v[248:249]
	s_nop 0
	s_nop 0
	s_nop 0
	s_nop 0
	v_cvt_pk_bf16_f32 v8, v8, v9
	s_nop 0
	s_nop 0
	s_nop 0
	s_nop 0
	v_cvt_pk_bf16_f32 v9, v10, v11
	v_add_u32_e32 v10, 0x2c010, v164
	v_mov_b32_e32 v11, v165
	v_lshl_add_u64 v[10:11], v[10:11], 1, s[36:37]
	global_store_dwordx2 v[10:11], v[8:9], off
	v_pk_mul_f32 v[246:247], v[240:241], v[4:5]
	v_pk_mul_f32 v[248:249], v[240:241], v[6:7]
	v_pk_fma_f32 v[246:247], v[4:5], v[246:247], v[244:245]
	v_pk_fma_f32 v[248:249], v[6:7], v[248:249], v[244:245]
	v_pk_mul_f32 v[246:247], v[4:5], v[246:247]
	v_pk_mul_f32 v[248:249], v[6:7], v[248:249]
	v_pk_mul_f32 v[246:247], v[242:243], v[246:247]
	v_pk_mul_f32 v[248:249], v[242:243], v[248:249]
	v_exp_f32_e32 v246, v246
	v_exp_f32_e32 v247, v247
	v_exp_f32_e32 v248, v248
	v_exp_f32_e32 v249, v249
	v_pk_add_f32 v[246:247], v[246:247], v[244:245]
	v_pk_add_f32 v[248:249], v[248:249], v[244:245]
	v_rcp_f32_e32 v246, v246
	v_rcp_f32_e32 v247, v247
	v_rcp_f32_e32 v248, v248
	v_rcp_f32_e32 v249, v249
	v_pk_mul_f32 v[4:5], v[4:5], v[246:247]
	v_pk_mul_f32 v[6:7], v[6:7], v[248:249]
	v_add_u32_e32 v8, 0x2c080, v164
	v_add_u32_e32 v164, 0x2c090, v164
	s_nop 0
	s_nop 0
	s_nop 0
	v_cvt_pk_bf16_f32 v4, v4, v5
	s_nop 0
	s_nop 0
	s_nop 0
	s_nop 0
	v_mov_b32_e32 v9, v165
	v_cvt_pk_bf16_f32 v5, v6, v7
	v_lshl_add_u64 v[6:7], v[8:9], 1, s[36:37]
	global_store_dwordx2 v[6:7], v[4:5], off
	v_pk_mul_f32 v[246:247], v[240:241], v[0:1]
	v_pk_mul_f32 v[248:249], v[240:241], v[2:3]
	v_pk_fma_f32 v[246:247], v[0:1], v[246:247], v[244:245]
	v_pk_fma_f32 v[248:249], v[2:3], v[248:249], v[244:245]
	v_pk_mul_f32 v[246:247], v[0:1], v[246:247]
	v_pk_mul_f32 v[248:249], v[2:3], v[248:249]
	v_pk_mul_f32 v[246:247], v[242:243], v[246:247]
	v_pk_mul_f32 v[248:249], v[242:243], v[248:249]
	v_exp_f32_e32 v246, v246
	v_exp_f32_e32 v247, v247
	v_exp_f32_e32 v248, v248
	v_exp_f32_e32 v249, v249
	v_pk_add_f32 v[246:247], v[246:247], v[244:245]
	v_pk_add_f32 v[248:249], v[248:249], v[244:245]
	v_rcp_f32_e32 v246, v246
	v_rcp_f32_e32 v247, v247
	v_rcp_f32_e32 v248, v248
	v_rcp_f32_e32 v249, v249
	v_pk_mul_f32 v[0:1], v[0:1], v[246:247]
	v_pk_mul_f32 v[2:3], v[2:3], v[248:249]
	s_nop 0
	s_nop 0
	s_nop 0
	s_nop 0
	v_cvt_pk_bf16_f32 v0, v0, v1
	s_nop 0
	s_nop 0
	s_nop 0
	s_nop 0
	v_cvt_pk_bf16_f32 v1, v2, v3
	v_lshl_add_u64 v[2:3], v[164:165], 1, s[36:37]
	global_store_dwordx2 v[2:3], v[0:1], off
	s_cbranch_vccz .LBB0_889
	s_waitcnt vmcnt(0)
	s_cmpk_gt_u32 s2, 0xff
	s_cbranch_scc1 .LBB0_897
	s_barrier

.LBB0_903:
	v_readlane_b32 s2, v238, 23
	s_add_i32 s0, s0, s2
	v_or_b32_e32 v64, s0, v73
	v_readlane_b32 s0, v238, 19
	v_lshlrev_b32_e32 v64, 10, v64
	s_nop 0
	v_lshl_or_b32 v65, v72, 2, s0
	v_or3_b32 v164, v64, v65, s1
	v_mov_b32_e32 v240, 0x3d372713
	v_mov_b32_e32 v241, 0x3d372713
	v_mov_b32_e32 v242, 0xc0135761
	v_mov_b32_e32 v243, 0xc0135761
	v_mov_b32_e32 v244, 1.0
	v_mov_b32_e32 v245, 1.0
	v_pk_mul_f32 v[246:247], v[240:241], v[60:61]
	v_pk_mul_f32 v[248:249], v[240:241], v[62:63]
	v_pk_fma_f32 v[246:247], v[60:61], v[246:247], v[244:245]
	v_pk_fma_f32 v[248:249], v[62:63], v[248:249], v[244:245]
	v_pk_mul_f32 v[246:247], v[60:61], v[246:247]
	v_pk_mul_f32 v[248:249], v[62:63], v[248:249]
	v_pk_mul_f32 v[246:247], v[242:243], v[246:247]
	v_pk_mul_f32 v[248:249], v[242:243], v[248:249]
	v_exp_f32_e32 v246, v246
	v_exp_f32_e32 v247, v247
	v_exp_f32_e32 v248, v248
	v_exp_f32_e32 v249, v249
	v_pk_add_f32 v[246:247], v[246:247], v[244:245]
	v_pk_add_f32 v[248:249], v[248:249], v[244:245]
	v_rcp_f32_e32 v246, v246
	v_rcp_f32_e32 v247, v247
	v_rcp_f32_e32 v248, v248
	v_rcp_f32_e32 v249, v249
	v_pk_mul_f32 v[60:61], v[60:61], v[246:247]
	v_pk_mul_f32 v[62:63], v[62:63], v[248:249]
	s_nop 0
	s_nop 0
	s_nop 0
	s_nop 0
	v_cvt_pk_bf16_f32 v60, v60, v61
	s_nop 0
	s_nop 0
	s_nop 0
	s_nop 0
	v_cvt_pk_bf16_f32 v61, v62, v63
	v_lshl_add_u64 v[62:63], v[164:165], 1, s[36:37]
	global_store_dwordx2 v[62:63], v[60:61], off
	v_pk_mul_f32 v[246:247], v[240:241], v[56:57]
	v_pk_mul_f32 v[248:249], v[240:241], v[58:59]
	v_pk_fma_f32 v[246:247], v[56:57], v[246:247], v[244:245]
	v_pk_fma_f32 v[248:249], v[58:59], v[248:249], v[244:245]
	v_pk_mul_f32 v[246:247], v[56:57], v[246:247]
	v_pk_mul_f32 v[248:249], v[58:59], v[248:249]
	v_pk_mul_f32 v[246:247], v[242:243], v[246:247]
	v_pk_mul_f32 v[248:249], v[242:243], v[248:249]
	v_exp_f32_e32 v246, v246
	v_exp_f32_e32 v247, v247
	v_exp_f32_e32 v248, v248
	v_exp_f32_e32 v249, v249
	v_pk_add_f32 v[246:247], v[246:247], v[244:245]
	v_pk_add_f32 v[248:249], v[248:249], v[244:245]
	v_rcp_f32_e32 v246, v246
	v_rcp_f32_e32 v247, v247
	v_rcp_f32_e32 v248, v248
	v_rcp_f32_e32 v249, v249
	v_pk_mul_f32 v[56:57], v[56:57], v[246:247]
	v_pk_mul_f32 v[58:59], v[58:59], v[248:249]
	s_nop 0
	s_nop 0
	s_nop 0
	s_nop 0
	v_cvt_pk_bf16_f32 v56, v56, v57
	s_nop 0
	s_nop 0
	s_nop 0
	s_nop 0
	v_cvt_pk_bf16_f32 v57, v58, v59
	v_or_b32_e32 v58, 16, v164
	v_mov_b32_e32 v59, v165
	v_lshl_add_u64 v[58:59], v[58:59], 1, s[36:37]
	global_store_dwordx2 v[58:59], v[56:57], off
	v_pk_mul_f32 v[246:247], v[240:241], v[52:53]
	v_pk_mul_f32 v[248:249], v[240:241], v[54:55]
	v_pk_fma_f32 v[246:247], v[52:53], v[246:247], v[244:245]
	v_pk_fma_f32 v[248:249], v[54:55], v[248:249], v[244:245]
	v_pk_mul_f32 v[246:247], v[52:53], v[246:247]
	v_pk_mul_f32 v[248:249], v[54:55], v[248:249]
	v_pk_mul_f32 v[246:247], v[242:243], v[246:247]
	v_pk_mul_f32 v[248:249], v[242:243], v[248:249]
	v_exp_f32_e32 v246, v246
	v_exp_f32_e32 v247, v247
	v_exp_f32_e32 v248, v248
	v_exp_f32_e32 v249, v249
	v_pk_add_f32 v[246:247], v[246:247], v[244:245]
	v_pk_add_f32 v[248:249], v[248:249], v[244:245]
	v_rcp_f32_e32 v246, v246
	v_rcp_f32_e32 v247, v247
	v_rcp_f32_e32 v248, v248
	v_rcp_f32_e32 v249, v249
	v_pk_mul_f32 v[52:53], v[52:53], v[246:247]
	v_pk_mul_f32 v[54:55], v[54:55], v[248:249]
	v_add_u32_e32 v56, 0x4000, v164
	s_nop 0
	s_nop 0
	s_nop 0
	v_cvt_pk_bf16_f32 v52, v52, v53
	s_nop 0
	s_nop 0
	s_nop 0
	s_nop 0
	v_mov_b32_e32 v57, v165
	v_cvt_pk_bf16_f32 v53, v54, v55
	v_lshl_add_u64 v[54:55], v[56:57], 1, s[36:37]
	global_store_dwordx2 v[54:55], v[52:53], off
	v_pk_mul_f32 v[246:247], v[240:241], v[48:49]
	v_pk_mul_f32 v[248:249], v[240:241], v[50:51]
	v_pk_fma_f32 v[246:247], v[48:49], v[246:247], v[244:245]
	v_pk_fma_f32 v[248:249], v[50:51], v[248:249], v[244:245]
	v_pk_mul_f32 v[246:247], v[48:49], v[246:247]
	v_pk_mul_f32 v[248:249], v[50:51], v[248:249]
	v_pk_mul_f32 v[246:247], v[242:243], v[246:247]
	v_pk_mul_f32 v[248:249], v[242:243], v[248:249]
	v_exp_f32_e32 v246, v246
	v_exp_f32_e32 v247, v247
	v_exp_f32_e32 v248, v248
	v_exp_f32_e32 v249, v249
	v_pk_add_f32 v[246:247], v[246:247], v[244:245]
	v_pk_add_f32 v[248:249], v[248:249], v[244:245]
	v_rcp_f32_e32 v246, v246
	v_rcp_f32_e32 v247, v247
	v_rcp_f32_e32 v248, v248
	v_rcp_f32_e32 v249, v249
	v_pk_mul_f32 v[48:49], v[48:49], v[246:247]
	v_pk_mul_f32 v[50:51], v[50:51], v[248:249]
	s_nop 0
	s_nop 0
	s_nop 0
	s_nop 0
	v_cvt_pk_bf16_f32 v48, v48, v49
	s_nop 0
	s_nop 0
	s_nop 0
	s_nop 0
	v_cvt_pk_bf16_f32 v49, v50, v51
	v_add_u32_e32 v50, 0x4010, v164
	v_mov_b32_e32 v51, v165
	v_lshl_add_u64 v[50:51], v[50:51], 1, s[36:37]
	global_store_dwordx2 v[50:51], v[48:49], off
	v_pk_mul_f32 v[246:247], v[240:241], v[44:45]
	v_pk_mul_f32 v[248:249], v[240:241], v[46:47]
	v_pk_fma_f32 v[246:247], v[44:45], v[246:247], v[244:245]
	v_pk_fma_f32 v[248:249], v[46:47], v[248:249], v[244:245]
	v_pk_mul_f32 v[246:247], v[44:45], v[246:247]
	v_pk_mul_f32 v[248:249], v[46:47], v[248:249]
	v_pk_mul_f32 v[246:247], v[242:243], v[246:247]
	v_pk_mul_f32 v[248:249], v[242:243], v[248:249]
	v_exp_f32_e32 v246, v246
	v_exp_f32_e32 v247, v247
	v_exp_f32_e32 v248, v248
	v_exp_f32_e32 v249, v249
	v_pk_add_f32 v[246:247], v[246:247], v[244:245]
	v_pk_add_f32 v[248:249], v[248:249], v[244:245]
	v_rcp_f32_e32 v246, v246
	v_rcp_f32_e32 v247, v247
	v_rcp_f32_e32 v248, v248
	v_rcp_f32_e32 v249, v249
	v_pk_mul_f32 v[44:45], v[44:45], v[246:247]
	v_pk_mul_f32 v[46:47], v[46:47], v[248:249]
	v_add_u32_e32 v48, 0x8000, v164
	s_nop 0
	s_nop 0
	s_nop 0
	v_cvt_pk_bf16_f32 v44, v44, v45
	s_nop 0
	s_nop 0
	s_nop 0
	s_nop 0
	v_mov_b32_e32 v49, v165
	v_cvt_pk_bf16_f32 v45, v46, v47
	v_lshl_add_u64 v[46:47], v[48:49], 1, s[36:37]
	global_store_dwordx2 v[46:47], v[44:45], off
	v_pk_mul_f32 v[246:247], v[240:241], v[40:41]
	v_pk_mul_f32 v[248:249], v[240:241], v[42:43]
	v_pk_fma_f32 v[246:247], v[40:41], v[246:247], v[244:245]
	v_pk_fma_f32 v[248:249], v[42:43], v[248:249], v[244:245]
	v_pk_mul_f32 v[246:247], v[40:41], v[246:247]
	v_pk_mul_f32 v[248:249], v[42:43], v[248:249]
	v_pk_mul_f32 v[246:247], v[242:243], v[246:247]
	v_pk_mul_f32 v[248:249], v[242:243], v[248:249]
	v_exp_f32_e32 v246, v246
	v_exp_f32_e32 v247, v247
	v_exp_f32_e32 v248, v248
	v_exp_f32_e32 v249, v249
	v_pk_add_f32 v[246:247], v[246:247], v[244:245]
	v_pk_add_f32 v[248:249], v[248:249], v[244:245]
	v_rcp_f32_e32 v246, v246
	v_rcp_f32_e32 v247, v247
	v_rcp_f32_e32 v248, v248
	v_rcp_f32_e32 v249, v249
	v_pk_mul_f32 v[40:41], v[40:41], v[246:247]
	v_pk_mul_f32 v[42:43], v[42:43], v[248:249]
	s_nop 0
	s_nop 0
	s_nop 0
	s_nop 0
	v_cvt_pk_bf16_f32 v40, v40, v41
	s_nop 0
	s_nop 0
	s_nop 0
	s_nop 0
	v_cvt_pk_bf16_f32 v41, v42, v43
	v_add_u32_e32 v42, 0x8010, v164
	v_mov_b32_e32 v43, v165
	v_lshl_add_u64 v[42:43], v[42:43], 1, s[36:37]
	global_store_dwordx2 v[42:43], v[40:41], off
	v_pk_mul_f32 v[246:247], v[240:241], v[36:37]
	v_pk_mul_f32 v[248:249], v[240:241], v[38:39]
	v_pk_fma_f32 v[246:247], v[36:37], v[246:247], v[244:245]
	v_pk_fma_f32 v[248:249], v[38:39], v[248:249], v[244:245]
	v_pk_mul_f32 v[246:247], v[36:37], v[246:247]
	v_pk_mul_f32 v[248:249], v[38:39], v[248:249]
	v_pk_mul_f32 v[246:247], v[242:243], v[246:247]
	v_pk_mul_f32 v[248:249], v[242:243], v[248:249]
	v_exp_f32_e32 v246, v246
	v_exp_f32_e32 v247, v247
	v_exp_f32_e32 v248, v248
	v_exp_f32_e32 v249, v249
	v_pk_add_f32 v[246:247], v[246:247], v[244:245]
	v_pk_add_f32 v[248:249], v[248:249], v[244:245]
	v_rcp_f32_e32 v246, v246
	v_rcp_f32_e32 v247, v247
	v_rcp_f32_e32 v248, v248
	v_rcp_f32_e32 v249, v249
	v_pk_mul_f32 v[36:37], v[36:37], v[246:247]
	v_pk_mul_f32 v[38:39], v[38:39], v[248:249]
	v_add_u32_e32 v40, 0xc000, v164
	s_nop 0
	s_nop 0
	s_nop 0
	v_cvt_pk_bf16_f32 v36, v36, v37
	s_nop 0
	s_nop 0
	s_nop 0
	s_nop 0
	v_mov_b32_e32 v41, v165
	v_cvt_pk_bf16_f32 v37, v38, v39
	v_lshl_add_u64 v[38:39], v[40:41], 1, s[36:37]
	global_store_dwordx2 v[38:39], v[36:37], off
	v_pk_mul_f32 v[246:247], v[240:241], v[32:33]
	v_pk_mul_f32 v[248:249], v[240:241], v[34:35]
	v_pk_fma_f32 v[246:247], v[32:33], v[246:247], v[244:245]
	v_pk_fma_f32 v[248:249], v[34:35], v[248:249], v[244:245]
	v_pk_mul_f32 v[246:247], v[32:33], v[246:247]
	v_pk_mul_f32 v[248:249], v[34:35], v[248:249]
	v_pk_mul_f32 v[246:247], v[242:243], v[246:247]
	v_pk_mul_f32 v[248:249], v[242:243], v[248:249]
	v_exp_f32_e32 v246, v246
	v_exp_f32_e32 v247, v247
	v_exp_f32_e32 v248, v248
	v_exp_f32_e32 v249, v249
	v_pk_add_f32 v[246:247], v[246:247], v[244:245]
	v_pk_add_f32 v[248:249], v[248:249], v[244:245]
	v_rcp_f32_e32 v246, v246
	v_rcp_f32_e32 v247, v247
	v_rcp_f32_e32 v248, v248
	v_rcp_f32_e32 v249, v249
	v_pk_mul_f32 v[32:33], v[32:33], v[246:247]
	v_pk_mul_f32 v[34:35], v[34:35], v[248:249]
	s_nop 0
	s_nop 0
	s_nop 0
	s_nop 0
	v_cvt_pk_bf16_f32 v32, v32, v33
	s_nop 0
	s_nop 0
	s_nop 0
	s_nop 0
	v_cvt_pk_bf16_f32 v33, v34, v35
	v_add_u32_e32 v34, 0xc010, v164
	v_mov_b32_e32 v35, v165
	v_lshl_add_u64 v[34:35], v[34:35], 1, s[36:37]
	global_store_dwordx2 v[34:35], v[32:33], off
	v_pk_mul_f32 v[246:247], v[240:241], v[28:29]
	v_pk_mul_f32 v[248:249], v[240:241], v[30:31]
	v_pk_fma_f32 v[246:247], v[28:29], v[246:247], v[244:245]
	v_pk_fma_f32 v[248:249], v[30:31], v[248:249], v[244:245]
	v_pk_mul_f32 v[246:247], v[28:29], v[246:247]
	v_pk_mul_f32 v[248:249], v[30:31], v[248:249]
	v_pk_mul_f32 v[246:247], v[242:243], v[246:247]
	v_pk_mul_f32 v[248:249], v[242:243], v[248:249]
	v_exp_f32_e32 v246, v246
	v_exp_f32_e32 v247, v247
	v_exp_f32_e32 v248, v248
	v_exp_f32_e32 v249, v249
	v_pk_add_f32 v[246:247], v[246:247], v[244:245]
	v_pk_add_f32 v[248:249], v[248:249], v[244:245]
	v_rcp_f32_e32 v246, v246
	v_rcp_f32_e32 v247, v247
	v_rcp_f32_e32 v248, v248
	v_rcp_f32_e32 v249, v249
	v_pk_mul_f32 v[28:29], v[28:29], v[246:247]
	v_pk_mul_f32 v[30:31], v[30:31], v[248:249]
	v_add_u32_e32 v32, 0x20000, v164
	s_nop 0
	s_nop 0
	s_nop 0
	v_cvt_pk_bf16_f32 v28, v28, v29
	s_nop 0
	s_nop 0
	s_nop 0
	s_nop 0
	v_mov_b32_e32 v33, v165
	v_cvt_pk_bf16_f32 v29, v30, v31
	v_lshl_add_u64 v[30:31], v[32:33], 1, s[36:37]
	global_store_dwordx2 v[30:31], v[28:29], off
	v_pk_mul_f32 v[246:247], v[240:241], v[24:25]
	v_pk_mul_f32 v[248:249], v[240:241], v[26:27]
	v_pk_fma_f32 v[246:247], v[24:25], v[246:247], v[244:245]
	v_pk_fma_f32 v[248:249], v[26:27], v[248:249], v[244:245]
	v_pk_mul_f32 v[246:247], v[24:25], v[246:247]
	v_pk_mul_f32 v[248:249], v[26:27], v[248:249]
	v_pk_mul_f32 v[246:247], v[242:243], v[246:247]
	v_pk_mul_f32 v[248:249], v[242:243], v[248:249]
	v_exp_f32_e32 v246, v246
	v_exp_f32_e32 v247, v247
	v_exp_f32_e32 v248, v248
	v_exp_f32_e32 v249, v249
	v_pk_add_f32 v[246:247], v[246:247], v[244:245]
	v_pk_add_f32 v[248:249], v[248:249], v[244:245]
	v_rcp_f32_e32 v246, v246
	v_rcp_f32_e32 v247, v247
	v_rcp_f32_e32 v248, v248
	v_rcp_f32_e32 v249, v249
	v_pk_mul_f32 v[24:25], v[24:25], v[246:247]
	v_pk_mul_f32 v[26:27], v[26:27], v[248:249]
	s_nop 0
	s_nop 0
	s_nop 0
	s_nop 0
	v_cvt_pk_bf16_f32 v24, v24, v25
	s_nop 0
	s_nop 0
	s_nop 0
	s_nop 0
	v_cvt_pk_bf16_f32 v25, v26, v27
	v_add_u32_e32 v26, 0x20010, v164
	v_mov_b32_e32 v27, v165
	v_lshl_add_u64 v[26:27], v[26:27], 1, s[36:37]
	global_store_dwordx2 v[26:27], v[24:25], off
	v_pk_mul_f32 v[246:247], v[240:241], v[20:21]
	v_pk_mul_f32 v[248:249], v[240:241], v[22:23]
	v_pk_fma_f32 v[246:247], v[20:21], v[246:247], v[244:245]
	v_pk_fma_f32 v[248:249], v[22:23], v[248:249], v[244:245]
	v_pk_mul_f32 v[246:247], v[20:21], v[246:247]
	v_pk_mul_f32 v[248:249], v[22:23], v[248:249]
	v_pk_mul_f32 v[246:247], v[242:243], v[246:247]
	v_pk_mul_f32 v[248:249], v[242:243], v[248:249]
	v_exp_f32_e32 v246, v246
	v_exp_f32_e32 v247, v247
	v_exp_f32_e32 v248, v248
	v_exp_f32_e32 v249, v249
	v_pk_add_f32 v[246:247], v[246:247], v[244:245]
	v_pk_add_f32 v[248:249], v[248:249], v[244:245]
	v_rcp_f32_e32 v246, v246
	v_rcp_f32_e32 v247, v247
	v_rcp_f32_e32 v248, v248
	v_rcp_f32_e32 v249, v249
	v_pk_mul_f32 v[20:21], v[20:21], v[246:247]
	v_pk_mul_f32 v[22:23], v[22:23], v[248:249]
	v_add_u32_e32 v24, 0x24000, v164
	s_nop 0
	s_nop 0
	s_nop 0
	v_cvt_pk_bf16_f32 v20, v20, v21
	s_nop 0
	s_nop 0
	s_nop 0
	s_nop 0
	v_mov_b32_e32 v25, v165
	v_cvt_pk_bf16_f32 v21, v22, v23
	v_lshl_add_u64 v[22:23], v[24:25], 1, s[36:37]
	global_store_dwordx2 v[22:23], v[20:21], off
	v_pk_mul_f32 v[246:247], v[240:241], v[16:17]
	v_pk_mul_f32 v[248:249], v[240:241], v[18:19]
	v_pk_fma_f32 v[246:247], v[16:17], v[246:247], v[244:245]
	v_pk_fma_f32 v[248:249], v[18:19], v[248:249], v[244:245]
	v_pk_mul_f32 v[246:247], v[16:17], v[246:247]
	v_pk_mul_f32 v[248:249], v[18:19], v[248:249]
	v_pk_mul_f32 v[246:247], v[242:243], v[246:247]
	v_pk_mul_f32 v[248:249], v[242:243], v[248:249]
	v_exp_f32_e32 v246, v246
	v_exp_f32_e32 v247, v247
	v_exp_f32_e32 v248, v248
	v_exp_f32_e32 v249, v249
	v_pk_add_f32 v[246:247], v[246:247], v[244:245]
	v_pk_add_f32 v[248:249], v[248:249], v[244:245]
	v_rcp_f32_e32 v246, v246
	v_rcp_f32_e32 v247, v247
	v_rcp_f32_e32 v248, v248
	v_rcp_f32_e32 v249, v249
	v_pk_mul_f32 v[16:17], v[16:17], v[246:247]
	v_pk_mul_f32 v[18:19], v[18:19], v[248:249]
	s_nop 0
	s_nop 0
	s_nop 0
	s_nop 0
	v_cvt_pk_bf16_f32 v16, v16, v17
	s_nop 0
	s_nop 0
	s_nop 0
	s_nop 0
	v_cvt_pk_bf16_f32 v17, v18, v19
	v_add_u32_e32 v18, 0x24010, v164
	v_mov_b32_e32 v19, v165
	v_lshl_add_u64 v[18:19], v[18:19], 1, s[36:37]
	global_store_dwordx2 v[18:19], v[16:17], off
	v_pk_mul_f32 v[246:247], v[240:241], v[12:13]
	v_pk_mul_f32 v[248:249], v[240:241], v[14:15]
	v_pk_fma_f32 v[246:247], v[12:13], v[246:247], v[244:245]
	v_pk_fma_f32 v[248:249], v[14:15], v[248:249], v[244:245]
	v_pk_mul_f32 v[246:247], v[12:13], v[246:247]
	v_pk_mul_f32 v[248:249], v[14:15], v[248:249]
	v_pk_mul_f32 v[246:247], v[242:243], v[246:247]
	v_pk_mul_f32 v[248:249], v[242:243], v[248:249]
	v_exp_f32_e32 v246, v246
	v_exp_f32_e32 v247, v247
	v_exp_f32_e32 v248, v248
	v_exp_f32_e32 v249, v249
	v_pk_add_f32 v[246:247], v[246:247], v[244:245]
	v_pk_add_f32 v[248:249], v[248:249], v[244:245]
	v_rcp_f32_e32 v246, v246
	v_rcp_f32_e32 v247, v247
	v_rcp_f32_e32 v248, v248
	v_rcp_f32_e32 v249, v249
	v_pk_mul_f32 v[12:13], v[12:13], v[246:247]
	v_pk_mul_f32 v[14:15], v[14:15], v[248:249]
	v_add_u32_e32 v16, 0x28000, v164
	s_nop 0
	s_nop 0
	s_nop 0
	v_cvt_pk_bf16_f32 v12, v12, v13
	s_nop 0
	s_nop 0
	s_nop 0
	s_nop 0
	v_mov_b32_e32 v17, v165
	v_cvt_pk_bf16_f32 v13, v14, v15
	v_lshl_add_u64 v[14:15], v[16:17], 1, s[36:37]
	global_store_dwordx2 v[14:15], v[12:13], off
	v_pk_mul_f32 v[246:247], v[240:241], v[8:9]
	v_pk_mul_f32 v[248:249], v[240:241], v[10:11]
	v_pk_fma_f32 v[246:247], v[8:9], v[246:247], v[244:245]
	v_pk_fma_f32 v[248:249], v[10:11], v[248:249], v[244:245]
	v_pk_mul_f32 v[246:247], v[8:9], v[246:247]
	v_pk_mul_f32 v[248:249], v[10:11], v[248:249]
	v_pk_mul_f32 v[246:247], v[242:243], v[246:247]
	v_pk_mul_f32 v[248:249], v[242:243], v[248:249]
	v_exp_f32_e32 v246, v246
	v_exp_f32_e32 v247, v247
	v_exp_f32_e32 v248, v248
	v_exp_f32_e32 v249, v249
	v_pk_add_f32 v[246:247], v[246:247], v[244:245]
	v_pk_add_f32 v[248:249], v[248:249], v[244:245]
	v_rcp_f32_e32 v246, v246
	v_rcp_f32_e32 v247, v247
	v_rcp_f32_e32 v248, v248
	v_rcp_f32_e32 v249, v249
	v_pk_mul_f32 v[8:9], v[8:9], v[246:247]
	v_pk_mul_f32 v[10:11], v[10:11], v[248:249]
	s_nop 0
	s_nop 0
	s_nop 0
	s_nop 0
	v_cvt_pk_bf16_f32 v8, v8, v9
	s_nop 0
	s_nop 0
	s_nop 0
	s_nop 0
	v_cvt_pk_bf16_f32 v9, v10, v11
	v_add_u32_e32 v10, 0x28010, v164
	v_mov_b32_e32 v11, v165
	v_lshl_add_u64 v[10:11], v[10:11], 1, s[36:37]
	global_store_dwordx2 v[10:11], v[8:9], off
	v_pk_mul_f32 v[246:247], v[240:241], v[4:5]
	v_pk_mul_f32 v[248:249], v[240:241], v[6:7]
	v_pk_fma_f32 v[246:247], v[4:5], v[246:247], v[244:245]
	v_pk_fma_f32 v[248:249], v[6:7], v[248:249], v[244:245]
	v_pk_mul_f32 v[246:247], v[4:5], v[246:247]
	v_pk_mul_f32 v[248:249], v[6:7], v[248:249]
	v_pk_mul_f32 v[246:247], v[242:243], v[246:247]
	v_pk_mul_f32 v[248:249], v[242:243], v[248:249]
	v_exp_f32_e32 v246, v246
	v_exp_f32_e32 v247, v247
	v_exp_f32_e32 v248, v248
	v_exp_f32_e32 v249, v249
	v_pk_add_f32 v[246:247], v[246:247], v[244:245]
	v_pk_add_f32 v[248:249], v[248:249], v[244:245]
	v_rcp_f32_e32 v246, v246
	v_rcp_f32_e32 v247, v247
	v_rcp_f32_e32 v248, v248
	v_rcp_f32_e32 v249, v249
	v_pk_mul_f32 v[4:5], v[4:5], v[246:247]
	v_pk_mul_f32 v[6:7], v[6:7], v[248:249]
	v_add_u32_e32 v8, 0x2c000, v164
	v_add_u32_e32 v164, 0x2c010, v164
	s_nop 0
	s_nop 0
	s_nop 0
	v_cvt_pk_bf16_f32 v4, v4, v5
	s_nop 0
	s_nop 0
	s_nop 0
	s_nop 0
	v_mov_b32_e32 v9, v165
	v_cvt_pk_bf16_f32 v5, v6, v7
	v_lshl_add_u64 v[6:7], v[8:9], 1, s[36:37]
	global_store_dwordx2 v[6:7], v[4:5], off
	v_pk_mul_f32 v[246:247], v[240:241], v[0:1]
	v_pk_mul_f32 v[248:249], v[240:241], v[2:3]
	v_pk_fma_f32 v[246:247], v[0:1], v[246:247], v[244:245]
	v_pk_fma_f32 v[248:249], v[2:3], v[248:249], v[244:245]
	v_pk_mul_f32 v[246:247], v[0:1], v[246:247]
	v_pk_mul_f32 v[248:249], v[2:3], v[248:249]
	v_pk_mul_f32 v[246:247], v[242:243], v[246:247]
	v_pk_mul_f32 v[248:249], v[242:243], v[248:249]
	v_exp_f32_e32 v246, v246
	v_exp_f32_e32 v247, v247
	v_exp_f32_e32 v248, v248
	v_exp_f32_e32 v249, v249
	v_pk_add_f32 v[246:247], v[246:247], v[244:245]
	v_pk_add_f32 v[248:249], v[248:249], v[244:245]
	v_rcp_f32_e32 v246, v246
	v_rcp_f32_e32 v247, v247
	v_rcp_f32_e32 v248, v248
	v_rcp_f32_e32 v249, v249
	v_pk_mul_f32 v[0:1], v[0:1], v[246:247]
	v_pk_mul_f32 v[2:3], v[2:3], v[248:249]
	s_nop 0
	s_nop 0
	s_nop 0
	s_nop 0
	v_cvt_pk_bf16_f32 v0, v0, v1
	s_nop 0
	s_nop 0
	s_nop 0
	s_nop 0
	v_cvt_pk_bf16_f32 v1, v2, v3
	v_lshl_add_u64 v[2:3], v[164:165], 1, s[36:37]
	global_store_dwordx2 v[2:3], v[0:1], off
